# attention K/V staging loads use the saddr form (SGPR tile base + 32-bit VGPR offset): drops 14 VALU address instructions per tile
# speedup vs baseline: 1.3163x; 1.0005x over previous
; #define MFMA32(a, b, c) __builtin_amdgcn_mfma_f32_32x32x16_bf16((a), (b), (c), 0, 0, 0)
; DI float ex2(float x) { return __builtin_amdgcn_exp2f(x); }
; template <int DQK>
; DI void attn_item_c(const u16* __restrict__ Qp, int ldq, const u16* __restrict__ Kp, const u16* __restrict__ Vtp, int ldv,
;                     int nkt, int q0, float c, u16* Yp, int ldy, char* smem, bool dry) {
;     ...
;     const u16* k0 = Ks + r * KLD + 8 * h;
;     bf16x8 ka[3][2];
;     ka[0][0] = *(const bf16x8*)(k0); ka[0][1] = *(const bf16x8*)(k0 + 32 * KLD);
;     ka[1][0] = *(const bf16x8*)(k0 + 16); ka[1][1] = *(const bf16x8*)(k0 + 32 * KLD + 16);
;     bf16x8 pf[4];
;     u32x4 pk[4];
;     float ps = 0.f;
; #pragma unroll
;     for (int ks = 0; ks < NKS; ++ks) {
;       if (ks + 2 < NKS) {
;         ka[(ks + 2) % 3][0] = *(const bf16x8*)(k0 + 16 * (ks + 2));
;         ka[(ks + 2) % 3][1] = *(const bf16x8*)(k0 + 32 * KLD + 16 * (ks + 2));
;       }
;       __builtin_amdgcn_sched_barrier(0);
;       n0 = MFMA32(ka[ks % 3][0], qf[ks], n0); n1 = MFMA32(ka[ks % 3][1], qf[ks], n1);
;       {
;         constexpr int dummy0 = 0; (void)dummy0;
;         const int e_lo = (32 * ks) / NKS, e_hi = (32 * (ks + 1)) / NKS;
; #pragma unroll
;         for (int q = 0; q < 3; ++q) {
;           const int e = e_lo + q;
;           if (e < e_hi) {
;             if (e < 16) { s0[e & 15] = ex2(fmaf(s0[e & 15], c, -mc)); ps += s0[e & 15]; }
;             else        { s1[e & 15] = ex2(fmaf(s1[e & 15], c, -mc)); ps += s1[e & 15]; }
;           }
;         }
;       }
;       if (ks == 3)  { pk[0].x = pack2(s0[0], s0[1]);  pk[0].y = pack2(s0[2], s0[3]);   pk[0].z = pack2(s0[4], s0[5]);   pk[0].w = pack2(s0[6], s0[7]); }
;       if (ks == 6)  { pk[1].x = pack2(s0[8], s0[9]);  pk[1].y = pack2(s0[10], s0[11]); pk[1].z = pack2(s0[12], s0[13]); pk[1].w = pack2(s0[14], s0[15]); }
;       if (ks == 9)  { pk[2].x = pack2(s1[0], s1[1]);  pk[2].y = pack2(s1[2], s1[3]);   pk[2].z = pack2(s1[4], s1[5]);   pk[2].w = pack2(s1[6], s1[7]); }
;       if (ks == NKS - 1) { pk[3].x = pack2(s1[8], s1[9]);  pk[3].y = pack2(s1[10], s1[11]); pk[3].z = pack2(s1[12], s1[13]); pk[3].w = pack2(s1[14], s1[15]); }
;       __builtin_amdgcn_sched_barrier(0);
;     }
;     l += ps;
; #pragma unroll
;     for (int i = 0; i < 4; ++i) pf[i] = __builtin_bit_cast(bf16x8, pk[i]);
.LBB0_214:
	ds_read_b128 v[16:19], v219
	ds_read_b128 v[20:23], v219 offset:32
	ds_read_b128 v[24:27], v219 offset:12800
	ds_read_b128 v[28:31], v219 offset:64
	ds_read_b128 v[48:51], v219 offset:12832
	ds_read_b128 v[52:55], v219 offset:12864
	v_accvgpr_read_b32 v56, a238
	v_mul_f32_e32 v249, 0xbdd53b94, v216
	v_cmp_le_i32_e32 vcc, s45, v56
	s_waitcnt lgkmcnt(5)
	v_mfma_f32_32x32x16_bf16 a[80:95], v[16:19], v[96:99], 0
	v_fmamk_f32 v16, v32, 0x3dd53b94, v249
	v_exp_f32_e32 v191, v16
	v_fmamk_f32 v16, v33, 0x3dd53b94, v249
	v_exp_f32_e32 v192, v16
	s_waitcnt lgkmcnt(3)
	v_mfma_f32_32x32x16_bf16 a[64:79], v[24:27], v[96:99], 0
	ds_read_b128 v[16:19], v219 offset:96
	ds_read_b128 v[24:27], v219 offset:12896
	v_mfma_f32_32x32x16_bf16 a[80:95], v[20:23], v[100:103], a[80:95]
	v_fmamk_f32 v20, v34, 0x3dd53b94, v249
	v_exp_f32_e32 v193, v20
	v_fmamk_f32 v20, v35, 0x3dd53b94, v249
	v_exp_f32_e32 v198, v20
	v_fmamk_f32 v20, v36, 0x3dd53b94, v249
	v_exp_f32_e32 v199, v20
	s_waitcnt lgkmcnt(3)
	v_mfma_f32_32x32x16_bf16 a[64:79], v[48:51], v[100:103], a[64:79]
	ds_read_b128 v[20:23], v219 offset:128
	ds_read_b128 v[32:35], v219 offset:12928
	v_mfma_f32_32x32x16_bf16 a[80:95], v[28:31], v[104:107], a[80:95]
	v_fmamk_f32 v28, v37, 0x3dd53b94, v249
	v_exp_f32_e32 v200, v28
	v_fmamk_f32 v28, v38, 0x3dd53b94, v249
	v_exp_f32_e32 v201, v28
	v_fmamk_f32 v28, v39, 0x3dd53b94, v249
	v_exp_f32_e32 v202, v28
	s_waitcnt lgkmcnt(4)
	v_mfma_f32_32x32x16_bf16 a[64:79], v[52:55], v[104:107], a[64:79]
	ds_read_b128 v[28:31], v219 offset:160
	ds_read_b128 v[36:39], v219 offset:12960
	s_waitcnt lgkmcnt(5)
	v_mfma_f32_32x32x16_bf16 a[80:95], v[16:19], v[108:111], a[80:95]
	v_fmamk_f32 v16, v40, 0x3dd53b94, v249
	v_exp_f32_e32 v203, v16
	v_fmamk_f32 v16, v41, 0x3dd53b94, v249
	v_exp_f32_e32 v204, v16
	s_waitcnt lgkmcnt(4)
	v_mfma_f32_32x32x16_bf16 a[64:79], v[24:27], v[108:111], a[64:79]
	ds_read_b128 v[16:19], v219 offset:192
	ds_read_b128 v[24:27], v219 offset:12992
	s_waitcnt lgkmcnt(5)
	v_mfma_f32_32x32x16_bf16 a[80:95], v[20:23], v[112:115], a[80:95]
	v_fmamk_f32 v20, v42, 0x3dd53b94, v249
	v_exp_f32_e32 v205, v20
	v_fmamk_f32 v20, v43, 0x3dd53b94, v249
	v_exp_f32_e32 v206, v20
	v_fmamk_f32 v20, v44, 0x3dd53b94, v249
	v_exp_f32_e32 v207, v20
	s_waitcnt lgkmcnt(4)
	v_mfma_f32_32x32x16_bf16 a[64:79], v[32:35], v[112:115], a[64:79]
	ds_read_b128 v[20:23], v219 offset:224
	ds_read_b128 v[32:35], v219 offset:13024
	s_waitcnt lgkmcnt(5)
	v_mfma_f32_32x32x16_bf16 a[80:95], v[28:31], v[116:119], a[80:95]
	v_fmamk_f32 v28, v45, 0x3dd53b94, v249
	v_exp_f32_e32 v208, v28
	v_fmamk_f32 v28, v46, 0x3dd53b94, v249
	v_exp_f32_e32 v209, v28
	v_fmamk_f32 v28, v47, 0x3dd53b94, v249
	v_exp_f32_e32 v248, v28
	s_waitcnt lgkmcnt(4)
	v_mfma_f32_32x32x16_bf16 a[64:79], v[36:39], v[116:119], a[64:79]
	ds_read_b128 v[28:31], v219 offset:256
	ds_read_b128 v[36:39], v219 offset:13056
	s_waitcnt lgkmcnt(5)
	v_mfma_f32_32x32x16_bf16 a[80:95], v[16:19], v[120:123], a[80:95]
	v_fmamk_f32 v0, v0, 0x3dd53b94, v249
	v_exp_f32_e32 v213, v0
	v_fmamk_f32 v0, v1, 0x3dd53b94, v249
	v_exp_f32_e32 v214, v0
	s_waitcnt lgkmcnt(4)
	v_mfma_f32_32x32x16_bf16 a[64:79], v[24:27], v[120:123], a[64:79]
	ds_read_b128 v[16:19], v219 offset:288
	ds_read_b128 v[24:27], v219 offset:13088
	s_waitcnt lgkmcnt(5)
	v_mfma_f32_32x32x16_bf16 a[80:95], v[20:23], v[124:127], a[80:95]
	v_fmamk_f32 v0, v2, 0x3dd53b94, v249
	v_exp_f32_e32 v129, v0
	v_fmamk_f32 v0, v3, 0x3dd53b94, v249
	v_exp_f32_e32 v215, v0
	v_fmamk_f32 v0, v4, 0x3dd53b94, v249
	v_exp_f32_e32 v227, v0
	s_waitcnt lgkmcnt(4)
	v_mfma_f32_32x32x16_bf16 a[64:79], v[32:35], v[124:127], a[64:79]
	ds_read_b128 v[0:3], v219 offset:320
	ds_read_b128 v[20:23], v219 offset:13120
	s_waitcnt lgkmcnt(5)
	v_mfma_f32_32x32x16_bf16 a[80:95], v[28:31], v[130:133], a[80:95]
	v_fmamk_f32 v4, v5, 0x3dd53b94, v249
	v_exp_f32_e32 v228, v4
	v_fmamk_f32 v4, v6, 0x3dd53b94, v249
	v_exp_f32_e32 v229, v4
	v_fmamk_f32 v4, v7, 0x3dd53b94, v249
	v_exp_f32_e32 v230, v4
	s_waitcnt lgkmcnt(4)
	v_mfma_f32_32x32x16_bf16 a[64:79], v[36:39], v[130:133], a[64:79]
	ds_read_b128 v[4:7], v219 offset:352
	ds_read_b128 v[28:31], v219 offset:13152
	s_waitcnt lgkmcnt(5)
	v_mfma_f32_32x32x16_bf16 a[80:95], v[16:19], v[134:137], a[80:95]
	v_fmamk_f32 v8, v8, 0x3dd53b94, v249
	v_exp_f32_e32 v149, v8
	v_fmamk_f32 v8, v9, 0x3dd53b94, v249
	v_exp_f32_e32 v231, v8
	s_waitcnt lgkmcnt(4)
	v_mfma_f32_32x32x16_bf16 a[64:79], v[24:27], v[134:137], a[64:79]
	s_waitcnt lgkmcnt(3)
	v_mfma_f32_32x32x16_bf16 a[80:95], v[0:3], v[138:141], a[80:95]
	v_fmamk_f32 v0, v10, 0x3dd53b94, v249
	v_exp_f32_e32 v218, v0
	v_fmamk_f32 v0, v11, 0x3dd53b94, v249
	v_exp_f32_e32 v234, v0
	v_fmamk_f32 v0, v12, 0x3dd53b94, v249
	v_exp_f32_e32 v244, v0
	s_waitcnt lgkmcnt(2)
	v_mfma_f32_32x32x16_bf16 a[64:79], v[20:23], v[138:141], a[64:79]
	s_waitcnt lgkmcnt(1)
	v_mfma_f32_32x32x16_bf16 a[80:95], v[4:7], v[142:145], a[80:95]
	v_fmamk_f32 v0, v13, 0x3dd53b94, v249
	v_exp_f32_e32 v146, v0
	v_fmamk_f32 v0, v14, 0x3dd53b94, v249
	v_exp_f32_e32 v147, v0
	v_fmamk_f32 v0, v15, 0x3dd53b94, v249
	v_exp_f32_e32 v148, v0
	s_waitcnt lgkmcnt(0)
	v_mfma_f32_32x32x16_bf16 a[64:79], v[28:31], v[142:145], a[64:79]
	v_add_u32_e32 v211, 0x1000, v220
	v_add_u32_e32 v251, 0x2000, v220
	v_add_u32_e32 v210, 0x3000, v220
	s_and_saveexec_b64 s[0:1], vcc
	s_xor_b64 s[0:1], exec, s[0:1]
	s_cbranch_execz .LBB0_216
; template <int DQK>
; DI void attn_item_c(const u16* __restrict__ Qp, int ldq, const u16* __restrict__ Kp, const u16* __restrict__ Vtp, int ldv,
;                     int nkt, int q0, float c, u16* Yp, int ldy, char* smem, bool dry) {
;     ...
;   auto gload = [&](u32x4* ks_, u32x4* vs_, int j) {
;     const u16* kg = Kp + (size_t)(j + 1) * 64 * DQK;
; #pragma unroll
;     for (int i = 0; i < NKC; ++i) ks_[i] = *(const u32x4*)(kg + (size_t)(tid + 256 * i) * 8);
; #pragma unroll
;     for (int i = 0; i < 4; ++i) vs_[i] = *(const u32x4*)(Vtp + (size_t)j * 8192 + (size_t)(tid + 256 * i) * 8);
;   };
;   auto lstore = [&](const u32x4* ks_, const u32x4* vs_, u16* Lb) {
; #pragma unroll
;     for (int i = 0; i < NKC; ++i) *(u32x4*)(Lb + kso[i]) = ks_[i];
; #pragma unroll
;     for (int i = 0; i < 4; ++i) {
;       u16* dst = Lb + vso + (32 * i) * 72;
;       u32x2 lo = {vs_[i].x, vs_[i].y}, hi = {vs_[i].z, vs_[i].w};
;       *(u32x2*)dst = lo; *(u32x2*)(dst + 8) = hi;
;     }
;   };
;   auto gloadK = [&](u32x4* ks_, int j) {
;     const u16* kg = Kp + (size_t)(j + 1) * 64 * DQK;
; #pragma unroll
;     for (int i = 0; i < NKC; ++i) ks_[i] = *(const u32x4*)(kg + (size_t)(tid + 256 * i) * 8);
;   };
;   auto gloadV = [&](u32x4* vs_, int j) {
; #pragma unroll
;     for (int i = 0; i < 4; ++i) vs_[i] = *(const u32x4*)(Vtp + (size_t)j * 8192 + (size_t)(tid + 256 * i) * 8);
;   };
;   auto lstoreK = [&](const u32x4* ks_, u16* Lb) {
; #pragma unroll
;     ...
;     if (active) {
;       const u16* v0 = Vs + r * 72 + 8 * h;
;       bf16x8 va[2][4];
; #pragma unroll
;       for (int dt = 0; dt < 4; ++dt) va[0][dt] = *(const bf16x8*)(v0 + (32 * dt) * 72);
; #pragma unroll
;       for (int kk = 0; kk < 4; ++kk) {
;         if (kk < 3) {
; #pragma unroll
;           for (int dt = 0; dt < 4; ++dt) va[(kk + 1) & 1][dt] = *(const bf16x8*)(v0 + (32 * dt) * 72 + 16 * (kk + 1));
;         }
;         __builtin_amdgcn_sched_barrier(0);
; #pragma unroll
;         for (int dt = 0; dt < 4; ++dt) o[dt] = MFMA32(va[kk & 1][dt], pf[kk], o[dt]);
;         if (kk == 0) lstoreK(wk, Ln);
;         if (kk == 1) lstoreV(wv, Ln);
;         if (kk == 2) gloadK(wk, kt + 3);
;         if (kk == 3) gloadV(wv, kt + 3);
;         __builtin_amdgcn_sched_barrier(0);
;       }
;     } else {
;       lstore(wk, wv, Ln);
;       gload(wk, wv, kt + 3);
;     }
	ds_read_b128 v[16:19], v128 offset:25600
	ds_read_b128 v[20:23], v128 offset:25632
	ds_read_b128 v[24:27], v128 offset:30208
	ds_read_b128 v[28:31], v128 offset:30240
	ds_read_b128 v[32:35], v128 offset:34816
	ds_read_b128 v[36:39], v128 offset:34848
	ds_read_b128 v[40:43], v128 offset:39424
	ds_read_b128 v[44:47], v128 offset:39456
	s_or_b32 s20, s44, 3
	s_add_i32 s8, s44, 4
	v_cvt_pk_bf16_f32 v0, v149, v231
	v_cvt_pk_bf16_f32 v1, v218, v234
	v_cvt_pk_bf16_f32 v2, v244, v146
	v_cvt_pk_bf16_f32 v3, v147, v148
	v_cvt_pk_bf16_f32 v4, v213, v214
	v_cvt_pk_bf16_f32 v5, v129, v215
	v_cvt_pk_bf16_f32 v6, v227, v228
	v_cvt_pk_bf16_f32 v7, v229, v230
	v_cvt_pk_bf16_f32 v8, v203, v204
	v_cvt_pk_bf16_f32 v9, v205, v206
	v_cvt_pk_bf16_f32 v10, v207, v208
	v_cvt_pk_bf16_f32 v11, v209, v248
	v_cvt_pk_bf16_f32 v12, v191, v192
	v_cvt_pk_bf16_f32 v13, v193, v198
	v_cvt_pk_bf16_f32 v14, v199, v200
	v_cvt_pk_bf16_f32 v15, v201, v202
	s_lshl_b64 s[6:7], s[20:21], 14
	s_mul_hi_u32 s9, s8, 0x6000
	s_mulk_i32 s8, 0x6000
	s_waitcnt lgkmcnt(7)
	v_mfma_f32_32x32x16_bf16 a[0:15], v[16:19], v[12:15], a[0:15]
	s_waitcnt vmcnt(10)
	ds_write_b128 v221, a[96:99] offset:44032
	ds_write_b128 v222, a[100:103] offset:44032
	ds_write_b128 v223, a[104:107] offset:44032
	ds_write_b128 v224, a[108:111] offset:44032
	ds_write_b128 v225, a[112:115] offset:44032
	ds_write_b128 v226, a[116:119] offset:44032
	s_waitcnt lgkmcnt(11)
	v_mfma_f32_32x32x16_bf16 a[16:31], v[24:27], v[12:15], a[16:31]
	s_waitcnt lgkmcnt(9)
	v_mfma_f32_32x32x16_bf16 a[32:47], v[32:35], v[12:15], a[32:47]
	s_waitcnt lgkmcnt(7)
	v_mfma_f32_32x32x16_bf16 a[48:63], v[40:43], v[12:15], a[48:63]
	ds_read_b128 v[12:15], v128 offset:25664
	ds_read_b128 v[16:19], v128 offset:30272
	ds_read_b128 v[24:27], v128 offset:34880
	ds_read_b128 v[32:35], v128 offset:39488
	v_mfma_f32_32x32x16_bf16 a[0:15], v[20:23], v[8:11], a[0:15]
	v_accvgpr_read_b32 v20, a240
	v_accvgpr_read_b32 v21, a241
	v_accvgpr_read_b32 v22, a242
	v_accvgpr_read_b32 v23, a243
	ds_write2_b64 v220, v[20:21], v[22:23] offset1:2
	ds_write2_b64 v211, v[150:151], v[152:153] offset0:64 offset1:66
	ds_write2_b64 v251, v[154:155], v[156:157] offset0:128 offset1:130
	ds_write2_b64 v210, v[158:159], v[160:161] offset0:192 offset1:194
	v_mfma_f32_32x32x16_bf16 a[16:31], v[28:31], v[8:11], a[16:31]
	v_mfma_f32_32x32x16_bf16 a[32:47], v[36:39], v[8:11], a[32:47]
	s_waitcnt lgkmcnt(14)
	v_mfma_f32_32x32x16_bf16 a[48:63], v[44:47], v[8:11], a[48:63]
	ds_read_b128 v[8:11], v128 offset:25696
	ds_read_b128 v[20:23], v128 offset:30304
	ds_read_b128 v[28:31], v128 offset:34912
	ds_read_b128 v[36:39], v128 offset:39520
	s_add_u32 s8, s94, s8
	s_addc_u32 s9, s95, s9
	s_waitcnt lgkmcnt(11)
	v_mfma_f32_32x32x16_bf16 a[0:15], v[12:15], v[4:7], a[0:15]
	global_load_dwordx4 a[148:151], v236, s[8:9]
	global_load_dwordx4 a[152:155], v238, s[8:9]
	global_load_dwordx4 a[160:163], v240, s[8:9]
	global_load_dwordx4 a[168:171], v242, s[8:9]
	v_accvgpr_read_b32 v12, a230
	v_accvgpr_read_b32 v14, a232
	global_load_dwordx4 a[176:179], v12, s[8:9]
	global_load_dwordx4 a[184:187], v14, s[8:9]
	s_waitcnt lgkmcnt(10)
	v_mfma_f32_32x32x16_bf16 a[16:31], v[16:19], v[4:7], a[16:31]
	s_waitcnt lgkmcnt(9)
	v_mfma_f32_32x32x16_bf16 a[32:47], v[24:27], v[4:7], a[32:47]
	s_waitcnt lgkmcnt(8)
	v_mfma_f32_32x32x16_bf16 a[48:63], v[32:35], v[4:7], a[48:63]
	s_add_u32 s6, s60, s6
	s_addc_u32 s7, s61, s7
	s_waitcnt lgkmcnt(3)
	v_mfma_f32_32x32x16_bf16 a[0:15], v[8:11], v[0:3], a[0:15]
	s_waitcnt lgkmcnt(2)
	v_mfma_f32_32x32x16_bf16 a[16:31], v[20:23], v[0:3], a[16:31]
	s_waitcnt lgkmcnt(1)
	v_mfma_f32_32x32x16_bf16 a[32:47], v[28:31], v[0:3], a[32:47]
	s_waitcnt lgkmcnt(0)
	v_mfma_f32_32x32x16_bf16 a[48:63], v[36:39], v[0:3], a[48:63]
	global_load_dwordx4 v[178:181], v236, s[6:7]
	global_load_dwordx4 v[186:189], v238, s[6:7]
	global_load_dwordx4 v[182:185], v240, s[6:7]
	global_load_dwordx4 v[194:197], v242, s[6:7]
.LBB0_216:
	s_andn2_saveexec_b64 s[0:1], s[0:1]
	s_cbranch_execz .LBB0_218
	s_add_i32 s6, s44, 4
	s_or_b32 s20, s44, 3
	s_mul_hi_u32 s7, s6, 0x6000
	s_mulk_i32 s6, 0x6000
	v_accvgpr_read_b32 v0, a240
	s_add_u32 s6, s94, s6
	v_accvgpr_read_b32 v1, a241
	v_accvgpr_read_b32 v2, a242
	v_accvgpr_read_b32 v3, a243
	s_addc_u32 s7, s95, s7
	s_waitcnt vmcnt(10)
	ds_write_b128 v221, a[96:99] offset:44032
	ds_write_b128 v222, a[100:103] offset:44032
	ds_write_b128 v223, a[104:107] offset:44032
	ds_write_b128 v224, a[108:111] offset:44032
	ds_write_b128 v225, a[112:115] offset:44032
	ds_write_b128 v226, a[116:119] offset:44032
	ds_write2_b64 v220, v[0:1], v[2:3] offset1:2
	ds_write2_b64 v211, v[150:151], v[152:153] offset0:64 offset1:66
	ds_write2_b64 v251, v[154:155], v[156:157] offset0:128 offset1:130
	ds_write2_b64 v210, v[158:159], v[160:161] offset0:192 offset1:194
	global_load_dwordx4 a[148:151], v236, s[6:7]
	global_load_dwordx4 a[152:155], v238, s[6:7]
	global_load_dwordx4 a[160:163], v240, s[6:7]
	global_load_dwordx4 a[168:171], v242, s[6:7]
	v_accvgpr_read_b32 v0, a230
	global_load_dwordx4 a[176:179], v0, s[6:7]
	v_accvgpr_read_b32 v0, a232
	global_load_dwordx4 a[184:187], v0, s[6:7]
	s_lshl_b64 s[6:7], s[20:21], 14
	s_add_u32 s6, s60, s6
	s_addc_u32 s7, s61, s7
	global_load_dwordx4 v[178:181], v236, s[6:7]
	global_load_dwordx4 v[186:189], v238, s[6:7]
	global_load_dwordx4 v[182:185], v240, s[6:7]
	global_load_dwordx4 v[194:197], v242, s[6:7]

; template <int DQK>
; DI void attn_item_c(const u16* __restrict__ Qp, int ldq, const u16* __restrict__ Kp, const u16* __restrict__ Vtp, int ldv,
;                     int nkt, int q0, float c, u16* Yp, int ldy, char* smem, bool dry) {
;     ...
;   auto body = [&](int kt, u32x4* wk, u32x4* wv, f32x16& s0, f32x16& s1, f32x16& n0, f32x16& n1) {
;     const u16* Ks = L0 + (kt & 1) * BUFE;
;     const u16* Vs = Ks + 64 * KLD;
;     u16* Ln = L0 + ((kt + 1) & 1) * BUFE;
;     const bool active = !(kt * 64 > qmin + 31);
;     if (kt * 64 + 63 > qmin) {
; #pragma unroll
;       for (int e = 0; e < 16; ++e) {
;         int key = kt * 64 + crow(e, h);
;         if (key > qi) s0[e] = -INFINITY;
;         if (key + 32 > qi) s1[e] = -INFINITY;
;       }
;     }
;     float mx = fmaxf(s0[0], s1[0]);
; #pragma unroll
;     for (int e = 1; e < 16; ++e) mx = fmaxf(fmaxf(mx, s0[e]), s1[e]);
;     mx = fmaxf(mx, __shfl_xor(mx, 32));
;     if (__builtin_amdgcn_ballot_w64((mx - m) * c > 8.f) != 0ull) {
;       const float mn = fmaxf(m, mx);
;       const float alpha = ex2((m - mn) * c);
;       m = mn;
;       l *= alpha;
; #pragma unroll
;       for (int dt = 0; dt < 4; ++dt)
; #pragma unroll
;         for (int e = 0; e < 16; ++e) o[dt][e] *= alpha;
;     }
;     const float mc = m * c;
; #pragma unroll
;     for (int e = 0; e < 16; ++e) { n0[e] = 0.f; n1[e] = 0.f; }
;     const u16* k0 = Ks + r * KLD + 8 * h;
;     bf16x8 ka[3][2];
;     ka[0][0] = *(const bf16x8*)(k0); ka[0][1] = *(const bf16x8*)(k0 + 32 * KLD);
;     ka[1][0] = *(const bf16x8*)(k0 + 16); ka[1][1] = *(const bf16x8*)(k0 + 32 * KLD + 16);
;     bf16x8 pf[4];
;     u32x4 pk[4];
;     float ps = 0.f;
; #pragma unroll
;     for (int ks = 0; ks < NKS; ++ks) {
;       if (ks + 2 < NKS) {
;         ka[(ks + 2) % 3][0] = *(const bf16x8*)(k0 + 16 * (ks + 2));
;         ka[(ks + 2) % 3][1] = *(const bf16x8*)(k0 + 32 * KLD + 16 * (ks + 2));
;       }
;       __builtin_amdgcn_sched_barrier(0);
;       n0 = MFMA32(ka[ks % 3][0], qf[ks], n0); n1 = MFMA32(ka[ks % 3][1], qf[ks], n1);
;       {
;         constexpr int dummy0 = 0; (void)dummy0;
;         const int e_lo = (32 * ks) / NKS, e_hi = (32 * (ks + 1)) / NKS;
; #pragma unroll
;         for (int q = 0; q < 3; ++q) {
;           const int e = e_lo + q;
;           if (e < e_hi) {
;             if (e < 16) { s0[e & 15] = ex2(fmaf(s0[e & 15], c, -mc)); ps += s0[e & 15]; }
.LBB0_224:
	ds_read_b128 v[18:21], v235 offset:44032
	ds_read_b128 v[22:25], v235 offset:44064
	ds_read_b128 v[26:29], v235 offset:56832
	ds_read_b128 v[48:51], v235 offset:44096
	ds_read_b128 v[52:55], v235 offset:56864
	ds_read_b128 v[56:59], v235 offset:56896
	v_accvgpr_read_b32 v17, a238
	v_mov_b32_e32 v16, v249
	v_cmp_le_i32_e32 vcc, s20, v17
	s_waitcnt lgkmcnt(5)
	v_mfma_f32_32x32x16_bf16 a[80:95], v[18:21], v[96:99], 0
	v_fmamk_f32 v17, v32, 0x3dd53b94, v16
	v_exp_f32_e32 v147, v17
	v_fmamk_f32 v17, v33, 0x3dd53b94, v16
	v_exp_f32_e32 v148, v17
	s_waitcnt lgkmcnt(3)
	v_mfma_f32_32x32x16_bf16 a[64:79], v[26:29], v[96:99], 0
	ds_read_b128 v[18:21], v235 offset:44128
	ds_read_b128 v[26:29], v235 offset:56928
	v_mfma_f32_32x32x16_bf16 a[80:95], v[22:25], v[100:103], a[80:95]
	v_fmamk_f32 v17, v34, 0x3dd53b94, v16
	v_exp_f32_e32 v149, v17
	v_fmamk_f32 v17, v35, 0x3dd53b94, v16
	v_exp_f32_e32 v150, v17
	v_fmamk_f32 v17, v36, 0x3dd53b94, v16
	v_exp_f32_e32 v151, v17
	s_waitcnt lgkmcnt(3)
	v_mfma_f32_32x32x16_bf16 a[64:79], v[52:55], v[100:103], a[64:79]
	ds_read_b128 v[22:25], v235 offset:44160
	ds_read_b128 v[30:33], v235 offset:56960
	v_mfma_f32_32x32x16_bf16 a[80:95], v[48:51], v[104:107], a[80:95]
	v_fmamk_f32 v17, v37, 0x3dd53b94, v16
	v_exp_f32_e32 v152, v17
	v_fmamk_f32 v17, v38, 0x3dd53b94, v16
	v_exp_f32_e32 v153, v17
	v_fmamk_f32 v17, v39, 0x3dd53b94, v16
	v_exp_f32_e32 v154, v17
	s_waitcnt lgkmcnt(4)
	v_mfma_f32_32x32x16_bf16 a[64:79], v[56:59], v[104:107], a[64:79]
	ds_read_b128 v[34:37], v235 offset:44192
	ds_read_b128 v[48:51], v235 offset:56992
	s_waitcnt lgkmcnt(5)
	v_mfma_f32_32x32x16_bf16 a[80:95], v[18:21], v[108:111], a[80:95]
	v_fmamk_f32 v17, v40, 0x3dd53b94, v16
	v_exp_f32_e32 v155, v17
	v_fmamk_f32 v17, v41, 0x3dd53b94, v16
	v_exp_f32_e32 v156, v17
	s_waitcnt lgkmcnt(4)
	v_mfma_f32_32x32x16_bf16 a[64:79], v[26:29], v[108:111], a[64:79]
	ds_read_b128 v[18:21], v235 offset:44224
	ds_read_b128 v[26:29], v235 offset:57024
	s_waitcnt lgkmcnt(5)
	v_mfma_f32_32x32x16_bf16 a[80:95], v[22:25], v[112:115], a[80:95]
	v_fmamk_f32 v17, v42, 0x3dd53b94, v16
	v_exp_f32_e32 v157, v17
	v_fmamk_f32 v17, v43, 0x3dd53b94, v16
	v_exp_f32_e32 v158, v17
	v_fmamk_f32 v17, v44, 0x3dd53b94, v16
	v_exp_f32_e32 v159, v17
	s_waitcnt lgkmcnt(4)
	v_mfma_f32_32x32x16_bf16 a[64:79], v[30:33], v[112:115], a[64:79]
	ds_read_b128 v[22:25], v235 offset:44256
	ds_read_b128 v[30:33], v235 offset:57056
	s_waitcnt lgkmcnt(5)
	v_mfma_f32_32x32x16_bf16 a[80:95], v[34:37], v[116:119], a[80:95]
	v_fmamk_f32 v17, v45, 0x3dd53b94, v16
	v_exp_f32_e32 v160, v17
	v_fmamk_f32 v17, v46, 0x3dd53b94, v16
	v_exp_f32_e32 v161, v17
	v_fmamk_f32 v17, v47, 0x3dd53b94, v16
	v_exp_f32_e32 v248, v17
	s_waitcnt lgkmcnt(4)
	v_mfma_f32_32x32x16_bf16 a[64:79], v[48:51], v[116:119], a[64:79]
	ds_read_b128 v[34:37], v235 offset:44288
	ds_read_b128 v[38:41], v235 offset:57088
	s_waitcnt lgkmcnt(5)
	v_mfma_f32_32x32x16_bf16 a[80:95], v[18:21], v[120:123], a[80:95]
	v_fmamk_f32 v0, v0, 0x3dd53b94, v16
	v_exp_f32_e32 v213, v0
	v_fmamk_f32 v0, v1, 0x3dd53b94, v16
	v_exp_f32_e32 v214, v0
	s_waitcnt lgkmcnt(4)
	v_mfma_f32_32x32x16_bf16 a[64:79], v[26:29], v[120:123], a[64:79]
	ds_read_b128 v[18:21], v235 offset:44320
	ds_read_b128 v[26:29], v235 offset:57120
	s_waitcnt lgkmcnt(5)
	v_mfma_f32_32x32x16_bf16 a[80:95], v[22:25], v[124:127], a[80:95]
	v_fmamk_f32 v0, v2, 0x3dd53b94, v16
	v_exp_f32_e32 v129, v0
	v_fmamk_f32 v0, v3, 0x3dd53b94, v16
	v_exp_f32_e32 v215, v0
	v_fmamk_f32 v0, v4, 0x3dd53b94, v16
	v_exp_f32_e32 v227, v0
	s_waitcnt lgkmcnt(4)
	v_mfma_f32_32x32x16_bf16 a[64:79], v[30:33], v[124:127], a[64:79]
	ds_read_b128 v[0:3], v235 offset:44352
	ds_read_b128 v[22:25], v235 offset:57152
	s_waitcnt lgkmcnt(5)
	v_mfma_f32_32x32x16_bf16 a[80:95], v[34:37], v[130:133], a[80:95]
	v_fmamk_f32 v4, v5, 0x3dd53b94, v16
	v_exp_f32_e32 v228, v4
	v_fmamk_f32 v4, v6, 0x3dd53b94, v16
	v_exp_f32_e32 v229, v4
	v_fmamk_f32 v4, v7, 0x3dd53b94, v16
	v_exp_f32_e32 v230, v4
	s_waitcnt lgkmcnt(4)
	v_mfma_f32_32x32x16_bf16 a[64:79], v[38:41], v[130:133], a[64:79]
	ds_read_b128 v[4:7], v235 offset:44384
	ds_read_b128 v[30:33], v235 offset:57184
	s_waitcnt lgkmcnt(5)
	v_mfma_f32_32x32x16_bf16 a[80:95], v[18:21], v[134:137], a[80:95]
	v_fmamk_f32 v8, v8, 0x3dd53b94, v16
	v_exp_f32_e32 v244, v8
	v_fmamk_f32 v8, v9, 0x3dd53b94, v16
	v_exp_f32_e32 v245, v8
	s_waitcnt lgkmcnt(4)
	v_mfma_f32_32x32x16_bf16 a[64:79], v[26:29], v[134:137], a[64:79]
	s_waitcnt lgkmcnt(3)
	v_mfma_f32_32x32x16_bf16 a[80:95], v[0:3], v[138:141], a[80:95]
	v_fmamk_f32 v0, v10, 0x3dd53b94, v16
	v_exp_f32_e32 v246, v0
	v_fmamk_f32 v0, v11, 0x3dd53b94, v16
	v_exp_f32_e32 v247, v0
	v_fmamk_f32 v0, v12, 0x3dd53b94, v16
	v_exp_f32_e32 v162, v0
	s_waitcnt lgkmcnt(2)
	v_mfma_f32_32x32x16_bf16 a[64:79], v[22:25], v[138:141], a[64:79]
	s_waitcnt lgkmcnt(1)
	v_mfma_f32_32x32x16_bf16 a[80:95], v[4:7], v[142:145], a[80:95]
	v_fmamk_f32 v0, v13, 0x3dd53b94, v16
	v_exp_f32_e32 v231, v0
	v_fmamk_f32 v0, v14, 0x3dd53b94, v16
	v_fmac_f32_e32 v16, 0x3dd53b94, v15
	v_exp_f32_e32 v234, v0
	v_exp_f32_e32 v218, v16
	s_waitcnt lgkmcnt(0)
	v_mfma_f32_32x32x16_bf16 a[64:79], v[30:33], v[142:145], a[64:79]
	s_and_saveexec_b64 s[0:1], vcc
	s_xor_b64 s[0:1], exec, s[0:1]
	s_cbranch_execz .LBB0_226
; template <int DQK>
; DI void attn_item_c(const u16* __restrict__ Qp, int ldq, const u16* __restrict__ Kp, const u16* __restrict__ Vtp, int ldv,
;                     int nkt, int q0, float c, u16* Yp, int ldy, char* smem, bool dry) {
;     ...
;   auto gload = [&](u32x4* ks_, u32x4* vs_, int j) {
;     const u16* kg = Kp + (size_t)(j + 1) * 64 * DQK;
; #pragma unroll
;     for (int i = 0; i < NKC; ++i) ks_[i] = *(const u32x4*)(kg + (size_t)(tid + 256 * i) * 8);
; #pragma unroll
;     for (int i = 0; i < 4; ++i) vs_[i] = *(const u32x4*)(Vtp + (size_t)j * 8192 + (size_t)(tid + 256 * i) * 8);
;   };
;   auto lstore = [&](const u32x4* ks_, const u32x4* vs_, u16* Lb) {
; #pragma unroll
;     for (int i = 0; i < NKC; ++i) *(u32x4*)(Lb + kso[i]) = ks_[i];
; #pragma unroll
;     for (int i = 0; i < 4; ++i) {
;       u16* dst = Lb + vso + (32 * i) * 72;
;       u32x2 lo = {vs_[i].x, vs_[i].y}, hi = {vs_[i].z, vs_[i].w};
;       *(u32x2*)dst = lo; *(u32x2*)(dst + 8) = hi;
;     }
;   };
;   auto gloadK = [&](u32x4* ks_, int j) {
;     const u16* kg = Kp + (size_t)(j + 1) * 64 * DQK;
; #pragma unroll
;     for (int i = 0; i < NKC; ++i) ks_[i] = *(const u32x4*)(kg + (size_t)(tid + 256 * i) * 8);
;   };
;   auto gloadV = [&](u32x4* vs_, int j) {
; #pragma unroll
;     for (int i = 0; i < 4; ++i) vs_[i] = *(const u32x4*)(Vtp + (size_t)j * 8192 + (size_t)(tid + 256 * i) * 8);
;   };
;   auto lstoreK = [&](const u32x4* ks_, u16* Lb) {
; #pragma unroll
;     ...
;     if (active) {
;       const u16* v0 = Vs + r * 72 + 8 * h;
;       bf16x8 va[2][4];
; #pragma unroll
;       for (int dt = 0; dt < 4; ++dt) va[0][dt] = *(const bf16x8*)(v0 + (32 * dt) * 72);
; #pragma unroll
;       for (int kk = 0; kk < 4; ++kk) {
;         if (kk < 3) {
; #pragma unroll
;           for (int dt = 0; dt < 4; ++dt) va[(kk + 1) & 1][dt] = *(const bf16x8*)(v0 + (32 * dt) * 72 + 16 * (kk + 1));
;         }
;         __builtin_amdgcn_sched_barrier(0);
; #pragma unroll
;         for (int dt = 0; dt < 4; ++dt) o[dt] = MFMA32(va[kk & 1][dt], pf[kk], o[dt]);
;         if (kk == 0) lstoreK(wk, Ln);
;         if (kk == 1) lstoreV(wv, Ln);
;         if (kk == 2) gloadK(wk, kt + 3);
;         if (kk == 3) gloadV(wv, kt + 3);
;         __builtin_amdgcn_sched_barrier(0);
;       }
;     } else {
;       lstore(wk, wv, Ln);
;       gload(wk, wv, kt + 3);
;     }
	ds_read_b128 v[16:19], v250
	ds_read_b128 v[20:23], v250 offset:32
	ds_read_b128 v[24:27], v250 offset:4608
	ds_read_b128 v[28:31], v250 offset:4640
	ds_read_b128 v[32:35], v250 offset:9216
	ds_read_b128 v[36:39], v250 offset:9248
	ds_read_b128 v[40:43], v250 offset:13824
	ds_read_b128 v[44:47], v250 offset:13856
	s_add_i32 s20, s44, 4
	s_add_i32 s8, s44, 5
	v_cvt_pk_bf16_f32 v0, v244, v245
	v_cvt_pk_bf16_f32 v1, v246, v247
	v_cvt_pk_bf16_f32 v2, v162, v231
	v_cvt_pk_bf16_f32 v3, v234, v218
	v_cvt_pk_bf16_f32 v4, v213, v214
	v_cvt_pk_bf16_f32 v5, v129, v215
	v_cvt_pk_bf16_f32 v6, v227, v228
	v_cvt_pk_bf16_f32 v7, v229, v230
	v_cvt_pk_bf16_f32 v8, v155, v156
	v_cvt_pk_bf16_f32 v9, v157, v158
	v_cvt_pk_bf16_f32 v10, v159, v160
	v_cvt_pk_bf16_f32 v11, v161, v248
	v_cvt_pk_bf16_f32 v12, v147, v148
	v_cvt_pk_bf16_f32 v13, v149, v150
	v_cvt_pk_bf16_f32 v14, v151, v152
	v_cvt_pk_bf16_f32 v15, v153, v154
	s_lshl_b64 s[6:7], s[20:21], 14
	s_mul_hi_u32 s9, s8, 0x6000
	s_mulk_i32 s8, 0x6000
	s_waitcnt lgkmcnt(7)
	v_mfma_f32_32x32x16_bf16 a[0:15], v[16:19], v[12:15], a[0:15]
	s_waitcnt vmcnt(10)
	ds_write_b128 v221, a[120:123]
	ds_write_b128 v222, a[124:127]
	ds_write_b128 v223, a[132:135]
	ds_write_b128 v224, a[136:139]
	ds_write_b128 v225, a[140:143]
	ds_write_b128 v226, a[144:147]
	s_waitcnt lgkmcnt(11)
	v_mfma_f32_32x32x16_bf16 a[16:31], v[24:27], v[12:15], a[16:31]
	s_waitcnt lgkmcnt(9)
	v_mfma_f32_32x32x16_bf16 a[32:47], v[32:35], v[12:15], a[32:47]
	s_waitcnt lgkmcnt(7)
	v_mfma_f32_32x32x16_bf16 a[48:63], v[40:43], v[12:15], a[48:63]
	ds_read_b128 v[12:15], v250 offset:64
	ds_read_b128 v[16:19], v250 offset:4672
	ds_read_b128 v[24:27], v250 offset:9280
	ds_read_b128 v[32:35], v250 offset:13888
	v_mfma_f32_32x32x16_bf16 a[0:15], v[20:23], v[8:11], a[0:15]
	v_accvgpr_read_b32 v20, a229
	v_mfma_f32_32x32x16_bf16 a[16:31], v[28:31], v[8:11], a[16:31]
	v_accvgpr_read_b32 v28, a244
	v_accvgpr_read_b32 v29, a245
	v_accvgpr_read_b32 v30, a246
	v_accvgpr_read_b32 v31, a247
	ds_write2_b64 v20, v[28:29], v[30:31] offset0:128 offset1:130
	v_accvgpr_read_b32 v20, a234
	ds_write2_b64 v20, v[170:171], v[172:173] offset0:192 offset1:194
	v_mfma_f32_32x32x16_bf16 a[32:47], v[36:39], v[8:11], a[32:47]
	v_accvgpr_read_b32 v20, a235
	ds_write2_b64 v20, v[166:167], v[168:169] offset1:2
	v_accvgpr_read_b32 v20, a236
	ds_write2_b64 v20, v[174:175], v[176:177] offset0:64 offset1:66
	s_waitcnt lgkmcnt(14)
	v_mfma_f32_32x32x16_bf16 a[48:63], v[44:47], v[8:11], a[48:63]
	ds_read_b128 v[8:11], v250 offset:96
	ds_read_b128 v[20:23], v250 offset:4704
	ds_read_b128 v[28:31], v250 offset:9312
	ds_read_b128 v[36:39], v250 offset:13920
	s_add_u32 s8, s94, s8
	s_addc_u32 s9, s95, s9
	s_waitcnt lgkmcnt(11)
	v_mfma_f32_32x32x16_bf16 a[0:15], v[12:15], v[4:7], a[0:15]
	global_load_dwordx4 a[156:159], v236, s[8:9]
	global_load_dwordx4 a[164:167], v238, s[8:9]
	global_load_dwordx4 a[172:175], v240, s[8:9]
	global_load_dwordx4 a[180:183], v242, s[8:9]
	v_accvgpr_read_b32 v12, a230
	v_accvgpr_read_b32 v14, a232
	global_load_dwordx4 a[188:191], v12, s[8:9]
	global_load_dwordx4 a[192:195], v14, s[8:9]
	s_waitcnt lgkmcnt(10)
	v_mfma_f32_32x32x16_bf16 a[16:31], v[16:19], v[4:7], a[16:31]
	s_waitcnt lgkmcnt(9)
	v_mfma_f32_32x32x16_bf16 a[32:47], v[24:27], v[4:7], a[32:47]
	s_waitcnt lgkmcnt(8)
	v_mfma_f32_32x32x16_bf16 a[48:63], v[32:35], v[4:7], a[48:63]
	s_add_u32 s6, s60, s6
	s_addc_u32 s7, s61, s7
	s_waitcnt lgkmcnt(3)
	v_mfma_f32_32x32x16_bf16 a[0:15], v[8:11], v[0:3], a[0:15]
	s_waitcnt lgkmcnt(2)
	v_mfma_f32_32x32x16_bf16 a[16:31], v[20:23], v[0:3], a[16:31]
	s_waitcnt lgkmcnt(1)
	v_mfma_f32_32x32x16_bf16 a[32:47], v[28:31], v[0:3], a[32:47]
	s_waitcnt lgkmcnt(0)
	v_mfma_f32_32x32x16_bf16 a[48:63], v[36:39], v[0:3], a[48:63]
	global_load_dwordx4 v[190:193], v236, s[6:7]
	global_load_dwordx4 v[202:205], v238, s[6:7]
	global_load_dwordx4 v[198:201], v240, s[6:7]
	global_load_dwordx4 v[206:209], v242, s[6:7]
.LBB0_226:
	s_andn2_saveexec_b64 s[0:1], s[0:1]
	s_cbranch_execz .LBB0_228
	v_accvgpr_read_b32 v2, a244
	v_accvgpr_read_b32 v0, a229
	v_accvgpr_read_b32 v3, a245
	v_accvgpr_read_b32 v4, a246
	v_accvgpr_read_b32 v5, a247
	s_add_i32 s6, s44, 5
	s_waitcnt vmcnt(10)
	ds_write_b128 v221, a[120:123]
	ds_write_b128 v222, a[124:127]
	ds_write_b128 v223, a[132:135]
	ds_write_b128 v224, a[136:139]
	ds_write_b128 v225, a[140:143]
	ds_write_b128 v226, a[144:147]
	ds_write2_b64 v0, v[2:3], v[4:5] offset0:128 offset1:130
	v_accvgpr_read_b32 v0, a234
	s_add_i32 s20, s44, 4
	s_mul_hi_u32 s7, s6, 0x6000
	s_mulk_i32 s6, 0x6000
	ds_write2_b64 v0, v[170:171], v[172:173] offset0:192 offset1:194
	v_accvgpr_read_b32 v0, a235
	s_add_u32 s6, s94, s6
	ds_write2_b64 v0, v[166:167], v[168:169] offset1:2
	v_accvgpr_read_b32 v0, a236
	s_addc_u32 s7, s95, s7
	ds_write2_b64 v0, v[174:175], v[176:177] offset0:64 offset1:66
	global_load_dwordx4 a[156:159], v236, s[6:7]
	global_load_dwordx4 a[164:167], v238, s[6:7]
	global_load_dwordx4 a[172:175], v240, s[6:7]
	global_load_dwordx4 a[180:183], v242, s[6:7]
	v_accvgpr_read_b32 v0, a230
	global_load_dwordx4 a[188:191], v0, s[6:7]
	v_accvgpr_read_b32 v0, a232
	global_load_dwordx4 a[192:195], v0, s[6:7]
	s_lshl_b64 s[6:7], s[20:21], 14
	s_add_u32 s6, s60, s6
	s_addc_u32 s7, s61, s7
	global_load_dwordx4 v[190:193], v236, s[6:7]
	global_load_dwordx4 v[202:205], v238, s[6:7]
	global_load_dwordx4 v[198:201], v240, s[6:7]
	global_load_dwordx4 v[206:209], v242, s[6:7]

; #define MFMA32(a, b, c) __builtin_amdgcn_mfma_f32_32x32x16_bf16((a), (b), (c), 0, 0, 0)
; DI float ex2(float x) { return __builtin_amdgcn_exp2f(x); }
; template <int DQK>
; DI void attn_item_c(const u16* __restrict__ Qp, int ldq, const u16* __restrict__ Kp, const u16* __restrict__ Vtp, int ldv,
;                     int nkt, int q0, float c, u16* Yp, int ldy, char* smem, bool dry) {
;     ...
;     const u16* k0 = Ks + r * KLD + 8 * h;
;     bf16x8 ka[3][2];
;     ka[0][0] = *(const bf16x8*)(k0); ka[0][1] = *(const bf16x8*)(k0 + 32 * KLD);
;     ka[1][0] = *(const bf16x8*)(k0 + 16); ka[1][1] = *(const bf16x8*)(k0 + 32 * KLD + 16);
;     bf16x8 pf[4];
;     u32x4 pk[4];
;     float ps = 0.f;
; #pragma unroll
;     for (int ks = 0; ks < NKS; ++ks) {
;       if (ks + 2 < NKS) {
;         ka[(ks + 2) % 3][0] = *(const bf16x8*)(k0 + 16 * (ks + 2));
;         ka[(ks + 2) % 3][1] = *(const bf16x8*)(k0 + 32 * KLD + 16 * (ks + 2));
;       }
;       __builtin_amdgcn_sched_barrier(0);
;       n0 = MFMA32(ka[ks % 3][0], qf[ks], n0); n1 = MFMA32(ka[ks % 3][1], qf[ks], n1);
;       {
;         constexpr int dummy0 = 0; (void)dummy0;
;         const int e_lo = (32 * ks) / NKS, e_hi = (32 * (ks + 1)) / NKS;
; #pragma unroll
;         for (int q = 0; q < 3; ++q) {
;           const int e = e_lo + q;
;           if (e < e_hi) {
;             if (e < 16) { s0[e & 15] = ex2(fmaf(s0[e & 15], c, -mc)); ps += s0[e & 15]; }
;             else        { s1[e & 15] = ex2(fmaf(s1[e & 15], c, -mc)); ps += s1[e & 15]; }
;           }
;         }
;       }
;       if (ks == 3)  { pk[0].x = pack2(s0[0], s0[1]);  pk[0].y = pack2(s0[2], s0[3]);   pk[0].z = pack2(s0[4], s0[5]);   pk[0].w = pack2(s0[6], s0[7]); }
;       if (ks == 6)  { pk[1].x = pack2(s0[8], s0[9]);  pk[1].y = pack2(s0[10], s0[11]); pk[1].z = pack2(s0[12], s0[13]); pk[1].w = pack2(s0[14], s0[15]); }
;       if (ks == 9)  { pk[2].x = pack2(s1[0], s1[1]);  pk[2].y = pack2(s1[2], s1[3]);   pk[2].z = pack2(s1[4], s1[5]);   pk[2].w = pack2(s1[6], s1[7]); }
;       if (ks == NKS - 1) { pk[3].x = pack2(s1[8], s1[9]);  pk[3].y = pack2(s1[10], s1[11]); pk[3].z = pack2(s1[12], s1[13]); pk[3].w = pack2(s1[14], s1[15]); }
;       __builtin_amdgcn_sched_barrier(0);
;     }
;     l += ps;
; #pragma unroll
;     for (int i = 0; i < 4; ++i) pf[i] = __builtin_bit_cast(bf16x8, pk[i]);
.LBB0_234:
	ds_read_b128 v[16:19], v219
	ds_read_b128 v[20:23], v219 offset:32
	ds_read_b128 v[24:27], v219 offset:12800
	ds_read_b128 v[28:31], v219 offset:64
	ds_read_b128 v[48:51], v219 offset:12832
	ds_read_b128 v[52:55], v219 offset:12864
	v_accvgpr_read_b32 v56, a238
	v_cmp_le_i32_e32 vcc, s20, v56
	s_waitcnt lgkmcnt(5)
	v_mfma_f32_32x32x16_bf16 a[80:95], v[16:19], v[96:99], 0
	v_fmamk_f32 v16, v32, 0x3dd53b94, v249
	v_exp_f32_e32 v162, v16
	v_fmamk_f32 v16, v33, 0x3dd53b94, v249
	v_exp_f32_e32 v163, v16
	s_waitcnt lgkmcnt(3)
	v_mfma_f32_32x32x16_bf16 a[64:79], v[24:27], v[96:99], 0
	ds_read_b128 v[16:19], v219 offset:96
	ds_read_b128 v[24:27], v219 offset:12896
	v_mfma_f32_32x32x16_bf16 a[80:95], v[20:23], v[100:103], a[80:95]
	v_fmamk_f32 v20, v34, 0x3dd53b94, v249
	v_exp_f32_e32 v164, v20
	v_fmamk_f32 v20, v35, 0x3dd53b94, v249
	v_exp_f32_e32 v165, v20
	v_fmamk_f32 v20, v36, 0x3dd53b94, v249
	v_exp_f32_e32 v166, v20
	s_waitcnt lgkmcnt(3)
	v_mfma_f32_32x32x16_bf16 a[64:79], v[48:51], v[100:103], a[64:79]
	ds_read_b128 v[20:23], v219 offset:128
	ds_read_b128 v[32:35], v219 offset:12928
	v_mfma_f32_32x32x16_bf16 a[80:95], v[28:31], v[104:107], a[80:95]
	v_fmamk_f32 v28, v37, 0x3dd53b94, v249
	v_exp_f32_e32 v167, v28
	v_fmamk_f32 v28, v38, 0x3dd53b94, v249
	v_exp_f32_e32 v168, v28
	v_fmamk_f32 v28, v39, 0x3dd53b94, v249
	v_exp_f32_e32 v169, v28
	s_waitcnt lgkmcnt(4)
	v_mfma_f32_32x32x16_bf16 a[64:79], v[52:55], v[104:107], a[64:79]
	ds_read_b128 v[28:31], v219 offset:160
	ds_read_b128 v[36:39], v219 offset:12960
	s_waitcnt lgkmcnt(5)
	v_mfma_f32_32x32x16_bf16 a[80:95], v[16:19], v[108:111], a[80:95]
	v_fmamk_f32 v16, v40, 0x3dd53b94, v249
	v_exp_f32_e32 v170, v16
	v_fmamk_f32 v16, v41, 0x3dd53b94, v249
	v_exp_f32_e32 v171, v16
	s_waitcnt lgkmcnt(4)
	v_mfma_f32_32x32x16_bf16 a[64:79], v[24:27], v[108:111], a[64:79]
	ds_read_b128 v[16:19], v219 offset:192
	ds_read_b128 v[24:27], v219 offset:12992
	s_waitcnt lgkmcnt(5)
	v_mfma_f32_32x32x16_bf16 a[80:95], v[20:23], v[112:115], a[80:95]
	v_fmamk_f32 v20, v42, 0x3dd53b94, v249
	v_exp_f32_e32 v172, v20
	v_fmamk_f32 v20, v43, 0x3dd53b94, v249
	v_exp_f32_e32 v173, v20
	v_fmamk_f32 v20, v44, 0x3dd53b94, v249
	v_exp_f32_e32 v174, v20
	s_waitcnt lgkmcnt(4)
	v_mfma_f32_32x32x16_bf16 a[64:79], v[32:35], v[112:115], a[64:79]
	ds_read_b128 v[20:23], v219 offset:224
	ds_read_b128 v[32:35], v219 offset:13024
	s_waitcnt lgkmcnt(5)
	v_mfma_f32_32x32x16_bf16 a[80:95], v[28:31], v[116:119], a[80:95]
	v_fmamk_f32 v28, v45, 0x3dd53b94, v249
	v_exp_f32_e32 v175, v28
	v_fmamk_f32 v28, v46, 0x3dd53b94, v249
	v_exp_f32_e32 v176, v28
	v_fmamk_f32 v28, v47, 0x3dd53b94, v249
	v_exp_f32_e32 v177, v28
	s_waitcnt lgkmcnt(4)
	v_mfma_f32_32x32x16_bf16 a[64:79], v[36:39], v[116:119], a[64:79]
	ds_read_b128 v[28:31], v219 offset:256
	ds_read_b128 v[36:39], v219 offset:13056
	s_waitcnt lgkmcnt(5)
	v_mfma_f32_32x32x16_bf16 a[80:95], v[16:19], v[120:123], a[80:95]
	v_fmamk_f32 v0, v0, 0x3dd53b94, v249
	v_exp_f32_e32 v213, v0
	v_fmamk_f32 v0, v1, 0x3dd53b94, v249
	v_exp_f32_e32 v214, v0
	s_waitcnt lgkmcnt(4)
	v_mfma_f32_32x32x16_bf16 a[64:79], v[24:27], v[120:123], a[64:79]
	ds_read_b128 v[16:19], v219 offset:288
	ds_read_b128 v[24:27], v219 offset:13088
	s_waitcnt lgkmcnt(5)
	v_mfma_f32_32x32x16_bf16 a[80:95], v[20:23], v[124:127], a[80:95]
	v_fmamk_f32 v0, v2, 0x3dd53b94, v249
	v_exp_f32_e32 v215, v0
	v_fmamk_f32 v0, v3, 0x3dd53b94, v249
	v_exp_f32_e32 v129, v0
	v_fmamk_f32 v0, v4, 0x3dd53b94, v249
	v_exp_f32_e32 v227, v0
	s_waitcnt lgkmcnt(4)
	v_mfma_f32_32x32x16_bf16 a[64:79], v[32:35], v[124:127], a[64:79]
	ds_read_b128 v[0:3], v219 offset:320
	ds_read_b128 v[20:23], v219 offset:13120
	s_waitcnt lgkmcnt(5)
	v_mfma_f32_32x32x16_bf16 a[80:95], v[28:31], v[130:133], a[80:95]
	v_fmamk_f32 v4, v5, 0x3dd53b94, v249
	v_exp_f32_e32 v228, v4
	v_fmamk_f32 v4, v6, 0x3dd53b94, v249
	v_exp_f32_e32 v229, v4
	v_fmamk_f32 v4, v7, 0x3dd53b94, v249
	v_exp_f32_e32 v230, v4
	s_waitcnt lgkmcnt(4)
	v_mfma_f32_32x32x16_bf16 a[64:79], v[36:39], v[130:133], a[64:79]
	ds_read_b128 v[4:7], v219 offset:352
	ds_read_b128 v[28:31], v219 offset:13152
	s_waitcnt lgkmcnt(5)
	v_mfma_f32_32x32x16_bf16 a[80:95], v[16:19], v[134:137], a[80:95]
	v_fmamk_f32 v8, v8, 0x3dd53b94, v249
	v_exp_f32_e32 v147, v8
	v_fmamk_f32 v8, v9, 0x3dd53b94, v249
	v_exp_f32_e32 v148, v8
	s_waitcnt lgkmcnt(4)
	v_mfma_f32_32x32x16_bf16 a[64:79], v[24:27], v[134:137], a[64:79]
	s_waitcnt lgkmcnt(3)
	v_mfma_f32_32x32x16_bf16 a[80:95], v[0:3], v[138:141], a[80:95]
	v_fmamk_f32 v0, v10, 0x3dd53b94, v249
	v_exp_f32_e32 v149, v0
	v_fmamk_f32 v0, v11, 0x3dd53b94, v249
	v_exp_f32_e32 v218, v0
	v_fmamk_f32 v0, v12, 0x3dd53b94, v249
	v_exp_f32_e32 v244, v0
	s_waitcnt lgkmcnt(2)
	v_mfma_f32_32x32x16_bf16 a[64:79], v[20:23], v[138:141], a[64:79]
	s_waitcnt lgkmcnt(1)
	v_mfma_f32_32x32x16_bf16 a[80:95], v[4:7], v[142:145], a[80:95]
	v_fmamk_f32 v0, v13, 0x3dd53b94, v249
	v_exp_f32_e32 v231, v0
	v_fmamk_f32 v0, v14, 0x3dd53b94, v249
	v_exp_f32_e32 v234, v0
	v_fmamk_f32 v0, v15, 0x3dd53b94, v249
	v_exp_f32_e32 v146, v0
	s_waitcnt lgkmcnt(0)
	v_mfma_f32_32x32x16_bf16 a[64:79], v[28:31], v[142:145], a[64:79]
	s_and_saveexec_b64 s[0:1], vcc
	s_xor_b64 s[0:1], exec, s[0:1]
	s_cbranch_execz .LBB0_236
; template <int DQK>
; DI void attn_item_c(const u16* __restrict__ Qp, int ldq, const u16* __restrict__ Kp, const u16* __restrict__ Vtp, int ldv,
;                     int nkt, int q0, float c, u16* Yp, int ldy, char* smem, bool dry) {
;     ...
;   auto gload = [&](u32x4* ks_, u32x4* vs_, int j) {
;     const u16* kg = Kp + (size_t)(j + 1) * 64 * DQK;
; #pragma unroll
;     for (int i = 0; i < NKC; ++i) ks_[i] = *(const u32x4*)(kg + (size_t)(tid + 256 * i) * 8);
; #pragma unroll
;     for (int i = 0; i < 4; ++i) vs_[i] = *(const u32x4*)(Vtp + (size_t)j * 8192 + (size_t)(tid + 256 * i) * 8);
;   };
;   auto lstore = [&](const u32x4* ks_, const u32x4* vs_, u16* Lb) {
; #pragma unroll
;     for (int i = 0; i < NKC; ++i) *(u32x4*)(Lb + kso[i]) = ks_[i];
; #pragma unroll
;     for (int i = 0; i < 4; ++i) {
;       u16* dst = Lb + vso + (32 * i) * 72;
;       u32x2 lo = {vs_[i].x, vs_[i].y}, hi = {vs_[i].z, vs_[i].w};
;       *(u32x2*)dst = lo; *(u32x2*)(dst + 8) = hi;
;     }
;   };
;   auto gloadK = [&](u32x4* ks_, int j) {
;     const u16* kg = Kp + (size_t)(j + 1) * 64 * DQK;
; #pragma unroll
;     for (int i = 0; i < NKC; ++i) ks_[i] = *(const u32x4*)(kg + (size_t)(tid + 256 * i) * 8);
;   };
;   auto gloadV = [&](u32x4* vs_, int j) {
; #pragma unroll
;     for (int i = 0; i < 4; ++i) vs_[i] = *(const u32x4*)(Vtp + (size_t)j * 8192 + (size_t)(tid + 256 * i) * 8);
;   };
;   auto lstoreK = [&](const u32x4* ks_, u16* Lb) {
; #pragma unroll
;     ...
;     if (active) {
;       const u16* v0 = Vs + r * 72 + 8 * h;
;       bf16x8 va[2][4];
; #pragma unroll
;       for (int dt = 0; dt < 4; ++dt) va[0][dt] = *(const bf16x8*)(v0 + (32 * dt) * 72);
; #pragma unroll
;       for (int kk = 0; kk < 4; ++kk) {
;         if (kk < 3) {
; #pragma unroll
;           for (int dt = 0; dt < 4; ++dt) va[(kk + 1) & 1][dt] = *(const bf16x8*)(v0 + (32 * dt) * 72 + 16 * (kk + 1));
;         }
;         __builtin_amdgcn_sched_barrier(0);
; #pragma unroll
;         for (int dt = 0; dt < 4; ++dt) o[dt] = MFMA32(va[kk & 1][dt], pf[kk], o[dt]);
;         if (kk == 0) lstoreK(wk, Ln);
;         if (kk == 1) lstoreV(wv, Ln);
;         if (kk == 2) gloadK(wk, kt + 3);
;         if (kk == 3) gloadV(wv, kt + 3);
;         __builtin_amdgcn_sched_barrier(0);
;       }
;     } else {
;       lstore(wk, wv, Ln);
;       gload(wk, wv, kt + 3);
;     }
	ds_read_b128 v[16:19], v128 offset:25600
	ds_read_b128 v[20:23], v128 offset:25632
	ds_read_b128 v[24:27], v128 offset:30208
	ds_read_b128 v[28:31], v128 offset:30240
	ds_read_b128 v[32:35], v128 offset:34816
	ds_read_b128 v[36:39], v128 offset:34848
	ds_read_b128 v[40:43], v128 offset:39424
	ds_read_b128 v[44:47], v128 offset:39456
	s_add_i32 s20, s44, 5
	s_add_i32 s8, s44, 6
	v_cvt_pk_bf16_f32 v0, v147, v148
	v_cvt_pk_bf16_f32 v1, v149, v218
	v_cvt_pk_bf16_f32 v2, v244, v231
	v_cvt_pk_bf16_f32 v3, v234, v146
	v_cvt_pk_bf16_f32 v4, v213, v214
	v_cvt_pk_bf16_f32 v5, v215, v129
	v_cvt_pk_bf16_f32 v6, v227, v228
	v_cvt_pk_bf16_f32 v7, v229, v230
	v_cvt_pk_bf16_f32 v8, v170, v171
	v_cvt_pk_bf16_f32 v9, v172, v173
	v_cvt_pk_bf16_f32 v10, v174, v175
	v_cvt_pk_bf16_f32 v11, v176, v177
	v_cvt_pk_bf16_f32 v12, v162, v163
	v_cvt_pk_bf16_f32 v13, v164, v165
	v_cvt_pk_bf16_f32 v14, v166, v167
	v_cvt_pk_bf16_f32 v15, v168, v169
	s_lshl_b64 s[6:7], s[20:21], 14
	s_mul_hi_u32 s9, s8, 0x6000
	s_mulk_i32 s8, 0x6000
	s_waitcnt lgkmcnt(7)
	v_mfma_f32_32x32x16_bf16 a[0:15], v[16:19], v[12:15], a[0:15]
	s_waitcnt vmcnt(10)
	ds_write_b128 v221, a[148:151] offset:44032
	ds_write_b128 v222, a[152:155] offset:44032
	ds_write_b128 v223, a[160:163] offset:44032
	ds_write_b128 v224, a[168:171] offset:44032
	ds_write_b128 v225, a[176:179] offset:44032
	ds_write_b128 v226, a[184:187] offset:44032
	s_waitcnt lgkmcnt(11)
	v_mfma_f32_32x32x16_bf16 a[16:31], v[24:27], v[12:15], a[16:31]
	s_waitcnt lgkmcnt(9)
	v_mfma_f32_32x32x16_bf16 a[32:47], v[32:35], v[12:15], a[32:47]
	s_waitcnt lgkmcnt(7)
	v_mfma_f32_32x32x16_bf16 a[48:63], v[40:43], v[12:15], a[48:63]
	ds_read_b128 v[12:15], v128 offset:25664
	ds_read_b128 v[16:19], v128 offset:30272
	ds_read_b128 v[24:27], v128 offset:34880
	ds_read_b128 v[32:35], v128 offset:39488
	v_mfma_f32_32x32x16_bf16 a[0:15], v[20:23], v[8:11], a[0:15]
	ds_write2_b64 v220, v[178:179], v[180:181] offset1:2
	ds_write2_b64 v211, v[186:187], v[188:189] offset0:64 offset1:66
	ds_write2_b64 v251, v[182:183], v[184:185] offset0:128 offset1:130
	ds_write2_b64 v210, v[194:195], v[196:197] offset0:192 offset1:194
	v_mfma_f32_32x32x16_bf16 a[16:31], v[28:31], v[8:11], a[16:31]
	v_mfma_f32_32x32x16_bf16 a[32:47], v[36:39], v[8:11], a[32:47]
	s_waitcnt lgkmcnt(14)
	v_mfma_f32_32x32x16_bf16 a[48:63], v[44:47], v[8:11], a[48:63]
	ds_read_b128 v[8:11], v128 offset:25696
	ds_read_b128 v[20:23], v128 offset:30304
	ds_read_b128 v[28:31], v128 offset:34912
	ds_read_b128 v[36:39], v128 offset:39520
	s_add_u32 s8, s94, s8
	s_addc_u32 s9, s95, s9
	s_waitcnt lgkmcnt(11)
	v_mfma_f32_32x32x16_bf16 a[0:15], v[12:15], v[4:7], a[0:15]
	global_load_dwordx4 a[96:99], v236, s[8:9]
	global_load_dwordx4 a[100:103], v238, s[8:9]
	global_load_dwordx4 a[104:107], v240, s[8:9]
	global_load_dwordx4 a[108:111], v242, s[8:9]
	v_accvgpr_read_b32 v12, a230
	v_accvgpr_read_b32 v14, a232
	global_load_dwordx4 a[112:115], v12, s[8:9]
	global_load_dwordx4 a[116:119], v14, s[8:9]
	s_waitcnt lgkmcnt(10)
	v_mfma_f32_32x32x16_bf16 a[16:31], v[16:19], v[4:7], a[16:31]
	s_waitcnt lgkmcnt(9)
	v_mfma_f32_32x32x16_bf16 a[32:47], v[24:27], v[4:7], a[32:47]
	s_waitcnt lgkmcnt(8)
	v_mfma_f32_32x32x16_bf16 a[48:63], v[32:35], v[4:7], a[48:63]
	s_add_u32 s6, s60, s6
	s_addc_u32 s7, s61, s7
	s_waitcnt lgkmcnt(3)
	v_mfma_f32_32x32x16_bf16 a[0:15], v[8:11], v[0:3], a[0:15]
	s_waitcnt lgkmcnt(2)
	v_mfma_f32_32x32x16_bf16 a[16:31], v[20:23], v[0:3], a[16:31]
	s_waitcnt lgkmcnt(1)
	v_mfma_f32_32x32x16_bf16 a[32:47], v[28:31], v[0:3], a[32:47]
	s_waitcnt lgkmcnt(0)
	v_mfma_f32_32x32x16_bf16 a[48:63], v[36:39], v[0:3], a[48:63]
	global_load_dwordx4 a[240:243], v236, s[6:7]
	global_load_dwordx4 v[150:153], v238, s[6:7]
	global_load_dwordx4 v[154:157], v240, s[6:7]
	global_load_dwordx4 v[158:161], v242, s[6:7]
.LBB0_236:
	s_andn2_saveexec_b64 s[0:1], s[0:1]
	s_cbranch_execz .LBB0_238
	s_add_i32 s6, s44, 6
	s_add_i32 s20, s44, 5
	s_mul_hi_u32 s7, s6, 0x6000
	s_mulk_i32 s6, 0x6000
	s_add_u32 s6, s94, s6
	s_addc_u32 s7, s95, s7
	s_waitcnt vmcnt(10)
	ds_write_b128 v221, a[148:151] offset:44032
	ds_write_b128 v222, a[152:155] offset:44032
	ds_write_b128 v223, a[160:163] offset:44032
	ds_write_b128 v224, a[168:171] offset:44032
	ds_write_b128 v225, a[176:179] offset:44032
	ds_write_b128 v226, a[184:187] offset:44032
	ds_write2_b64 v220, v[178:179], v[180:181] offset1:2
	ds_write2_b64 v211, v[186:187], v[188:189] offset0:64 offset1:66
	ds_write2_b64 v251, v[182:183], v[184:185] offset0:128 offset1:130
	ds_write2_b64 v210, v[194:195], v[196:197] offset0:192 offset1:194
	global_load_dwordx4 a[96:99], v236, s[6:7]
	global_load_dwordx4 a[100:103], v238, s[6:7]
	global_load_dwordx4 a[104:107], v240, s[6:7]
	global_load_dwordx4 a[108:111], v242, s[6:7]
	v_accvgpr_read_b32 v0, a230
	global_load_dwordx4 a[112:115], v0, s[6:7]
	v_accvgpr_read_b32 v0, a232
	global_load_dwordx4 a[116:119], v0, s[6:7]
	s_lshl_b64 s[6:7], s[20:21], 14
	s_add_u32 s6, s60, s6
	s_addc_u32 s7, s61, s7
	global_load_dwordx4 a[240:243], v236, s[6:7]
	global_load_dwordx4 v[150:153], v238, s[6:7]
	global_load_dwordx4 v[154:157], v240, s[6:7]
	global_load_dwordx4 v[158:161], v242, s[6:7]

; #define MFMA32(a, b, c) __builtin_amdgcn_mfma_f32_32x32x16_bf16((a), (b), (c), 0, 0, 0)
; DI float ex2(float x) { return __builtin_amdgcn_exp2f(x); }
; template <int DQK>
; DI void attn_item_c(const u16* __restrict__ Qp, int ldq, const u16* __restrict__ Kp, const u16* __restrict__ Vtp, int ldv,
;                     int nkt, int q0, float c, u16* Yp, int ldy, char* smem, bool dry) {
;     ...
;     const u16* k0 = Ks + r * KLD + 8 * h;
;     bf16x8 ka[3][2];
;     ka[0][0] = *(const bf16x8*)(k0); ka[0][1] = *(const bf16x8*)(k0 + 32 * KLD);
;     ka[1][0] = *(const bf16x8*)(k0 + 16); ka[1][1] = *(const bf16x8*)(k0 + 32 * KLD + 16);
;     bf16x8 pf[4];
;     u32x4 pk[4];
;     float ps = 0.f;
; #pragma unroll
;     for (int ks = 0; ks < NKS; ++ks) {
;       if (ks + 2 < NKS) {
;         ka[(ks + 2) % 3][0] = *(const bf16x8*)(k0 + 16 * (ks + 2));
;         ka[(ks + 2) % 3][1] = *(const bf16x8*)(k0 + 32 * KLD + 16 * (ks + 2));
;       }
;       __builtin_amdgcn_sched_barrier(0);
;       n0 = MFMA32(ka[ks % 3][0], qf[ks], n0); n1 = MFMA32(ka[ks % 3][1], qf[ks], n1);
;       {
;         constexpr int dummy0 = 0; (void)dummy0;
;         const int e_lo = (32 * ks) / NKS, e_hi = (32 * (ks + 1)) / NKS;
; #pragma unroll
;         for (int q = 0; q < 3; ++q) {
;           const int e = e_lo + q;
;           if (e < e_hi) {
;             if (e < 16) { s0[e & 15] = ex2(fmaf(s0[e & 15], c, -mc)); ps += s0[e & 15]; }
;             else        { s1[e & 15] = ex2(fmaf(s1[e & 15], c, -mc)); ps += s1[e & 15]; }
;           }
;         }
;       }
;       if (ks == 3)  { pk[0].x = pack2(s0[0], s0[1]);  pk[0].y = pack2(s0[2], s0[3]);   pk[0].z = pack2(s0[4], s0[5]);   pk[0].w = pack2(s0[6], s0[7]); }
;       if (ks == 6)  { pk[1].x = pack2(s0[8], s0[9]);  pk[1].y = pack2(s0[10], s0[11]); pk[1].z = pack2(s0[12], s0[13]); pk[1].w = pack2(s0[14], s0[15]); }
;       if (ks == 9)  { pk[2].x = pack2(s1[0], s1[1]);  pk[2].y = pack2(s1[2], s1[3]);   pk[2].z = pack2(s1[4], s1[5]);   pk[2].w = pack2(s1[6], s1[7]); }
;       if (ks == NKS - 1) { pk[3].x = pack2(s1[8], s1[9]);  pk[3].y = pack2(s1[10], s1[11]); pk[3].z = pack2(s1[12], s1[13]); pk[3].w = pack2(s1[14], s1[15]); }
;       __builtin_amdgcn_sched_barrier(0);
;     }
;     l += ps;
; #pragma unroll
;     for (int i = 0; i < 4; ++i) pf[i] = __builtin_bit_cast(bf16x8, pk[i]);
.LBB0_244:
	ds_read_b128 v[16:19], v235 offset:44032
	ds_read_b128 v[20:23], v235 offset:44064
	ds_read_b128 v[24:27], v235 offset:56832
	ds_read_b128 v[28:31], v235 offset:44096
	ds_read_b128 v[48:51], v235 offset:56864
	ds_read_b128 v[52:55], v235 offset:56896
	v_accvgpr_read_b32 v56, a238
	v_cmp_le_i32_e32 vcc, s20, v56
	s_waitcnt lgkmcnt(5)
	v_mfma_f32_32x32x16_bf16 a[80:95], v[16:19], v[96:99], 0
	v_fmamk_f32 v16, v32, 0x3dd53b94, v249
	v_fmamk_f32 v17, v33, 0x3dd53b94, v249
	v_exp_f32_e32 v16, v16
	v_exp_f32_e32 v17, v17
	s_waitcnt lgkmcnt(3)
	v_mfma_f32_32x32x16_bf16 a[64:79], v[24:27], v[96:99], 0
	ds_read_b128 v[24:27], v235 offset:44128
	ds_read_b128 v[56:59], v235 offset:56928
	v_mfma_f32_32x32x16_bf16 a[80:95], v[20:23], v[100:103], a[80:95]
	v_fmamk_f32 v18, v34, 0x3dd53b94, v249
	v_fmamk_f32 v19, v35, 0x3dd53b94, v249
	v_fmamk_f32 v20, v36, 0x3dd53b94, v249
	v_exp_f32_e32 v18, v18
	v_exp_f32_e32 v19, v19
	v_exp_f32_e32 v20, v20
	s_waitcnt lgkmcnt(3)
	v_mfma_f32_32x32x16_bf16 a[64:79], v[48:51], v[100:103], a[64:79]
	ds_read_b128 v[32:35], v235 offset:44160
	ds_read_b128 v[48:51], v235 offset:56960
	v_mfma_f32_32x32x16_bf16 a[80:95], v[28:31], v[104:107], a[80:95]
	v_fmamk_f32 v21, v37, 0x3dd53b94, v249
	v_fmamk_f32 v22, v38, 0x3dd53b94, v249
	v_fmamk_f32 v23, v39, 0x3dd53b94, v249
	v_exp_f32_e32 v21, v21
	v_exp_f32_e32 v22, v22
	v_exp_f32_e32 v23, v23
	s_waitcnt lgkmcnt(4)
	v_mfma_f32_32x32x16_bf16 a[64:79], v[52:55], v[104:107], a[64:79]
	ds_read_b128 v[36:39], v235 offset:44192
	ds_read_b128 v[52:55], v235 offset:56992
	s_waitcnt lgkmcnt(5)
	v_mfma_f32_32x32x16_bf16 a[80:95], v[24:27], v[108:111], a[80:95]
	v_fmamk_f32 v24, v40, 0x3dd53b94, v249
	v_fmamk_f32 v25, v41, 0x3dd53b94, v249
	v_exp_f32_e32 v24, v24
	v_exp_f32_e32 v25, v25
	s_waitcnt lgkmcnt(4)
	v_mfma_f32_32x32x16_bf16 a[64:79], v[56:59], v[108:111], a[64:79]
	ds_read_b128 v[56:59], v235 offset:44224
	ds_read_b128 v[60:63], v235 offset:57024
	s_waitcnt lgkmcnt(5)
	v_mfma_f32_32x32x16_bf16 a[80:95], v[32:35], v[112:115], a[80:95]
	v_fmamk_f32 v26, v42, 0x3dd53b94, v249
	v_fmamk_f32 v27, v43, 0x3dd53b94, v249
	v_fmamk_f32 v28, v44, 0x3dd53b94, v249
	v_exp_f32_e32 v26, v26
	v_exp_f32_e32 v27, v27
	v_exp_f32_e32 v28, v28
	s_waitcnt lgkmcnt(4)
	v_mfma_f32_32x32x16_bf16 a[64:79], v[48:51], v[112:115], a[64:79]
	ds_read_b128 v[32:35], v235 offset:44256
	ds_read_b128 v[40:43], v235 offset:57056
	s_waitcnt lgkmcnt(5)
	v_mfma_f32_32x32x16_bf16 a[80:95], v[36:39], v[116:119], a[80:95]
	v_fmamk_f32 v29, v45, 0x3dd53b94, v249
	v_fmamk_f32 v30, v46, 0x3dd53b94, v249
	v_fmamk_f32 v31, v47, 0x3dd53b94, v249
	v_exp_f32_e32 v29, v29
	v_exp_f32_e32 v30, v30
	v_exp_f32_e32 v31, v31
	s_waitcnt lgkmcnt(4)
	v_mfma_f32_32x32x16_bf16 a[64:79], v[52:55], v[116:119], a[64:79]
	ds_read_b128 v[36:39], v235 offset:44288
	ds_read_b128 v[44:47], v235 offset:57088
	s_waitcnt lgkmcnt(5)
	v_mfma_f32_32x32x16_bf16 a[80:95], v[56:59], v[120:123], a[80:95]
	v_fmamk_f32 v0, v0, 0x3dd53b94, v249
	v_fmamk_f32 v1, v1, 0x3dd53b94, v249
	v_exp_f32_e32 v0, v0
	v_exp_f32_e32 v1, v1
	s_waitcnt lgkmcnt(4)
	v_mfma_f32_32x32x16_bf16 a[64:79], v[60:63], v[120:123], a[64:79]
	ds_read_b128 v[48:51], v235 offset:44320
	ds_read_b128 v[52:55], v235 offset:57120
	s_waitcnt lgkmcnt(5)
	v_mfma_f32_32x32x16_bf16 a[80:95], v[32:35], v[124:127], a[80:95]
	v_fmamk_f32 v2, v2, 0x3dd53b94, v249
	v_fmamk_f32 v3, v3, 0x3dd53b94, v249
	v_fmamk_f32 v4, v4, 0x3dd53b94, v249
	v_exp_f32_e32 v2, v2
	v_exp_f32_e32 v3, v3
	v_exp_f32_e32 v4, v4
	s_waitcnt lgkmcnt(4)
	v_mfma_f32_32x32x16_bf16 a[64:79], v[40:43], v[124:127], a[64:79]
	ds_read_b128 v[32:35], v235 offset:44352
	ds_read_b128 v[40:43], v235 offset:57152
	s_waitcnt lgkmcnt(5)
	v_mfma_f32_32x32x16_bf16 a[80:95], v[36:39], v[130:133], a[80:95]
	v_fmamk_f32 v5, v5, 0x3dd53b94, v249
	v_fmamk_f32 v6, v6, 0x3dd53b94, v249
	v_fmamk_f32 v7, v7, 0x3dd53b94, v249
	v_exp_f32_e32 v5, v5
	v_exp_f32_e32 v6, v6
	v_exp_f32_e32 v7, v7
	s_waitcnt lgkmcnt(4)
	v_mfma_f32_32x32x16_bf16 a[64:79], v[44:47], v[130:133], a[64:79]
	ds_read_b128 v[36:39], v235 offset:44384
	ds_read_b128 v[44:47], v235 offset:57184
	s_waitcnt lgkmcnt(5)
	v_mfma_f32_32x32x16_bf16 a[80:95], v[48:51], v[134:137], a[80:95]
	v_fmamk_f32 v8, v8, 0x3dd53b94, v249
	v_fmamk_f32 v9, v9, 0x3dd53b94, v249
	v_exp_f32_e32 v8, v8
	v_exp_f32_e32 v9, v9
	s_waitcnt lgkmcnt(4)
	v_mfma_f32_32x32x16_bf16 a[64:79], v[52:55], v[134:137], a[64:79]
	s_waitcnt lgkmcnt(3)
	v_mfma_f32_32x32x16_bf16 a[80:95], v[32:35], v[138:141], a[80:95]
	v_fmamk_f32 v10, v10, 0x3dd53b94, v249
	v_fmamk_f32 v11, v11, 0x3dd53b94, v249
	v_fmamk_f32 v12, v12, 0x3dd53b94, v249
	v_exp_f32_e32 v10, v10
	v_exp_f32_e32 v11, v11
	v_exp_f32_e32 v12, v12
	s_waitcnt lgkmcnt(2)
	v_mfma_f32_32x32x16_bf16 a[64:79], v[40:43], v[138:141], a[64:79]
	s_waitcnt lgkmcnt(1)
	v_mfma_f32_32x32x16_bf16 a[80:95], v[36:39], v[142:145], a[80:95]
	v_fmamk_f32 v13, v13, 0x3dd53b94, v249
	v_fmamk_f32 v14, v14, 0x3dd53b94, v249
	v_fmamk_f32 v15, v15, 0x3dd53b94, v249
	v_exp_f32_e32 v13, v13
	v_exp_f32_e32 v14, v14
	v_exp_f32_e32 v15, v15
	s_waitcnt lgkmcnt(0)
	v_mfma_f32_32x32x16_bf16 a[64:79], v[44:47], v[142:145], a[64:79]
	s_and_saveexec_b64 s[0:1], vcc
	s_xor_b64 s[0:1], exec, s[0:1]
	s_cbranch_execz .LBB0_246
; template <int DQK>
; DI void attn_item_c(const u16* __restrict__ Qp, int ldq, const u16* __restrict__ Kp, const u16* __restrict__ Vtp, int ldv,
;                     int nkt, int q0, float c, u16* Yp, int ldy, char* smem, bool dry) {
;     ...
;   auto gload = [&](u32x4* ks_, u32x4* vs_, int j) {
;     const u16* kg = Kp + (size_t)(j + 1) * 64 * DQK;
; #pragma unroll
;     for (int i = 0; i < NKC; ++i) ks_[i] = *(const u32x4*)(kg + (size_t)(tid + 256 * i) * 8);
; #pragma unroll
;     for (int i = 0; i < 4; ++i) vs_[i] = *(const u32x4*)(Vtp + (size_t)j * 8192 + (size_t)(tid + 256 * i) * 8);
;   };
;   auto lstore = [&](const u32x4* ks_, const u32x4* vs_, u16* Lb) {
; #pragma unroll
;     for (int i = 0; i < NKC; ++i) *(u32x4*)(Lb + kso[i]) = ks_[i];
; #pragma unroll
;     for (int i = 0; i < 4; ++i) {
;       u16* dst = Lb + vso + (32 * i) * 72;
;       u32x2 lo = {vs_[i].x, vs_[i].y}, hi = {vs_[i].z, vs_[i].w};
;       *(u32x2*)dst = lo; *(u32x2*)(dst + 8) = hi;
;     }
;   };
;   auto gloadK = [&](u32x4* ks_, int j) {
;     const u16* kg = Kp + (size_t)(j + 1) * 64 * DQK;
; #pragma unroll
;     for (int i = 0; i < NKC; ++i) ks_[i] = *(const u32x4*)(kg + (size_t)(tid + 256 * i) * 8);
;   };
;     ...
;     if (active) {
;       const u16* v0 = Vs + r * 72 + 8 * h;
;       bf16x8 va[2][4];
; #pragma unroll
;       for (int dt = 0; dt < 4; ++dt) va[0][dt] = *(const bf16x8*)(v0 + (32 * dt) * 72);
; #pragma unroll
;       for (int kk = 0; kk < 4; ++kk) {
;         if (kk < 3) {
; #pragma unroll
;           for (int dt = 0; dt < 4; ++dt) va[(kk + 1) & 1][dt] = *(const bf16x8*)(v0 + (32 * dt) * 72 + 16 * (kk + 1));
;         }
;         __builtin_amdgcn_sched_barrier(0);
; #pragma unroll
;         for (int dt = 0; dt < 4; ++dt) o[dt] = MFMA32(va[kk & 1][dt], pf[kk], o[dt]);
;         if (kk == 0) lstoreK(wk, Ln);
;         if (kk == 1) lstoreV(wv, Ln);
;         if (kk == 2) gloadK(wk, kt + 3);
;         if (kk == 3) gloadV(wv, kt + 3);
;         __builtin_amdgcn_sched_barrier(0);
;       }
;     } else {
;       lstore(wk, wv, Ln);
;       gload(wk, wv, kt + 3);
;     }
;     __syncthreads();
;   };
;   for (int kt4 = 0; kt4 < nktp; kt4 += 4) {
;     body(kt4 + 0, kstB, vstB, sa0, sa1, sb0, sb1); body(kt4 + 1, kstA, vstA, sb0, sb1, sa0, sa1);
;     body(kt4 + 2, kstB, vstB, sa0, sa1, sb0, sb1); body(kt4 + 3, kstA, vstA, sb0, sb1, sa0, sa1);
;   }
	ds_read_b128 v[48:51], v250
	ds_read_b128 v[52:55], v250 offset:32
	ds_read_b128 v[56:59], v250 offset:4608
	ds_read_b128 v[60:63], v250 offset:4640
	ds_read_b128 v[64:67], v250 offset:9216
	ds_read_b128 v[68:71], v250 offset:9248
	ds_read_b128 v[72:75], v250 offset:13824
	ds_read_b128 v[76:79], v250 offset:13856
	s_add_i32 s20, s44, 6
	s_add_i32 s8, s44, 7
	v_cvt_pk_bf16_f32 v32, v8, v9
	v_cvt_pk_bf16_f32 v33, v10, v11
	v_cvt_pk_bf16_f32 v34, v12, v13
	v_cvt_pk_bf16_f32 v35, v14, v15
	v_cvt_pk_bf16_f32 v36, v0, v1
	v_cvt_pk_bf16_f32 v37, v2, v3
	v_cvt_pk_bf16_f32 v38, v4, v5
	v_cvt_pk_bf16_f32 v39, v6, v7
	v_cvt_pk_bf16_f32 v40, v24, v25
	v_cvt_pk_bf16_f32 v41, v26, v27
	v_cvt_pk_bf16_f32 v42, v28, v29
	v_cvt_pk_bf16_f32 v43, v30, v31
	v_cvt_pk_bf16_f32 v44, v16, v17
	v_cvt_pk_bf16_f32 v45, v18, v19
	v_cvt_pk_bf16_f32 v46, v20, v21
	v_cvt_pk_bf16_f32 v47, v22, v23
	s_lshl_b64 s[6:7], s[20:21], 14
	s_mul_hi_u32 s9, s8, 0x6000
	s_mulk_i32 s8, 0x6000
	s_waitcnt lgkmcnt(7)
	v_mfma_f32_32x32x16_bf16 a[0:15], v[48:51], v[44:47], a[0:15]
	s_waitcnt vmcnt(10)
	ds_write_b128 v221, a[156:159]
	ds_write_b128 v222, a[164:167]
	ds_write_b128 v223, a[172:175]
	ds_write_b128 v224, a[180:183]
	ds_write_b128 v225, a[188:191]
	ds_write_b128 v226, a[192:195]
	s_waitcnt lgkmcnt(11)
	v_mfma_f32_32x32x16_bf16 a[16:31], v[56:59], v[44:47], a[16:31]
	s_waitcnt lgkmcnt(9)
	v_mfma_f32_32x32x16_bf16 a[32:47], v[64:67], v[44:47], a[32:47]
	s_waitcnt lgkmcnt(7)
	v_mfma_f32_32x32x16_bf16 a[48:63], v[72:75], v[44:47], a[48:63]
	ds_read_b128 v[44:47], v250 offset:64
	ds_read_b128 v[48:51], v250 offset:4672
	ds_read_b128 v[56:59], v250 offset:9280
	ds_read_b128 v[64:67], v250 offset:13888
	v_mfma_f32_32x32x16_bf16 a[0:15], v[52:55], v[40:43], a[0:15]
	v_accvgpr_read_b32 v52, a229
	ds_write2_b64 v52, v[190:191], v[192:193] offset0:128 offset1:130
	v_accvgpr_read_b32 v52, a234
	ds_write2_b64 v52, v[202:203], v[204:205] offset0:192 offset1:194
	v_accvgpr_read_b32 v52, a235
	ds_write2_b64 v52, v[198:199], v[200:201] offset1:2
	v_accvgpr_read_b32 v52, a236
	v_mfma_f32_32x32x16_bf16 a[16:31], v[60:63], v[40:43], a[16:31]
	ds_write2_b64 v52, v[206:207], v[208:209] offset0:64 offset1:66
	v_mfma_f32_32x32x16_bf16 a[32:47], v[68:71], v[40:43], a[32:47]
	s_waitcnt lgkmcnt(14)
	v_mfma_f32_32x32x16_bf16 a[48:63], v[76:79], v[40:43], a[48:63]
	ds_read_b128 v[40:43], v250 offset:96
	ds_read_b128 v[52:55], v250 offset:4704
	ds_read_b128 v[60:63], v250 offset:9312
	ds_read_b128 v[68:71], v250 offset:13920
	s_add_u32 s8, s94, s8
	s_addc_u32 s9, s95, s9
	s_waitcnt lgkmcnt(11)
	v_mfma_f32_32x32x16_bf16 a[0:15], v[44:47], v[36:39], a[0:15]
	global_load_dwordx4 a[120:123], v236, s[8:9]
	global_load_dwordx4 a[124:127], v238, s[8:9]
	global_load_dwordx4 a[132:135], v240, s[8:9]
	global_load_dwordx4 a[136:139], v242, s[8:9]
	v_accvgpr_read_b32 v44, a230
	v_accvgpr_read_b32 v46, a232
	global_load_dwordx4 a[140:143], v44, s[8:9]
	global_load_dwordx4 a[144:147], v46, s[8:9]
	s_waitcnt lgkmcnt(10)
	v_mfma_f32_32x32x16_bf16 a[16:31], v[48:51], v[36:39], a[16:31]
	s_waitcnt lgkmcnt(9)
	v_mfma_f32_32x32x16_bf16 a[32:47], v[56:59], v[36:39], a[32:47]
	s_waitcnt lgkmcnt(8)
	v_mfma_f32_32x32x16_bf16 a[48:63], v[64:67], v[36:39], a[48:63]
	s_add_u32 s6, s60, s6
	s_addc_u32 s7, s61, s7
	s_waitcnt lgkmcnt(3)
	v_mfma_f32_32x32x16_bf16 a[0:15], v[40:43], v[32:35], a[0:15]
	s_waitcnt lgkmcnt(2)
	v_mfma_f32_32x32x16_bf16 a[16:31], v[52:55], v[32:35], a[16:31]
	s_waitcnt lgkmcnt(1)
	v_mfma_f32_32x32x16_bf16 a[32:47], v[60:63], v[32:35], a[32:47]
	s_waitcnt lgkmcnt(0)
	v_mfma_f32_32x32x16_bf16 a[48:63], v[68:71], v[32:35], a[48:63]
	global_load_dwordx4 a[244:247], v236, s[6:7]
	global_load_dwordx4 v[170:173], v238, s[6:7]
	global_load_dwordx4 v[166:169], v240, s[6:7]
	global_load_dwordx4 v[174:177], v242, s[6:7]
.LBB0_246:
	s_andn2_saveexec_b64 s[0:1], s[0:1]
	s_cbranch_execz .LBB0_207
	v_accvgpr_read_b32 v32, a229
	s_add_i32 s6, s44, 7
	s_waitcnt vmcnt(10)
	ds_write_b128 v221, a[156:159]
	ds_write_b128 v222, a[164:167]
	ds_write_b128 v223, a[172:175]
	ds_write_b128 v224, a[180:183]
	ds_write_b128 v225, a[188:191]
	ds_write_b128 v226, a[192:195]
	ds_write2_b64 v32, v[190:191], v[192:193] offset0:128 offset1:130
	v_accvgpr_read_b32 v32, a234
	s_add_i32 s20, s44, 6
	s_mul_hi_u32 s7, s6, 0x6000
	s_mulk_i32 s6, 0x6000
	ds_write2_b64 v32, v[202:203], v[204:205] offset0:192 offset1:194
	v_accvgpr_read_b32 v32, a235
	s_add_u32 s6, s94, s6
	ds_write2_b64 v32, v[198:199], v[200:201] offset1:2
	v_accvgpr_read_b32 v32, a236
	s_addc_u32 s7, s95, s7
	ds_write2_b64 v32, v[206:207], v[208:209] offset0:64 offset1:66
	global_load_dwordx4 a[120:123], v236, s[6:7]
	global_load_dwordx4 a[124:127], v238, s[6:7]
	global_load_dwordx4 a[132:135], v240, s[6:7]
	global_load_dwordx4 a[136:139], v242, s[6:7]
	v_accvgpr_read_b32 v32, a230
	global_load_dwordx4 a[140:143], v32, s[6:7]
	v_accvgpr_read_b32 v32, a232
	global_load_dwordx4 a[144:147], v32, s[6:7]
	s_lshl_b64 s[6:7], s[20:21], 14
	s_add_u32 s6, s60, s6
	s_addc_u32 s7, s61, s7
	global_load_dwordx4 a[244:247], v236, s[6:7]
	global_load_dwordx4 v[170:173], v238, s[6:7]
	global_load_dwordx4 v[166:169], v240, s[6:7]
	global_load_dwordx4 v[174:177], v242, s[6:7]
	s_branch .LBB0_207

; #define MFMA32(a, b, c) __builtin_amdgcn_mfma_f32_32x32x16_bf16((a), (b), (c), 0, 0, 0)
; DI float ex2(float x) { return __builtin_amdgcn_exp2f(x); }
; template <int DQK>
; DI void attn_item_c(const u16* __restrict__ Qp, int ldq, const u16* __restrict__ Kp, const u16* __restrict__ Vtp, int ldv,
;                     int nkt, int q0, float c, u16* Yp, int ldy, char* smem, bool dry) {
;     ...
;     const u16* k0 = Ks + r * KLD + 8 * h;
;     bf16x8 ka[3][2];
;     ka[0][0] = *(const bf16x8*)(k0); ka[0][1] = *(const bf16x8*)(k0 + 32 * KLD);
;     ka[1][0] = *(const bf16x8*)(k0 + 16); ka[1][1] = *(const bf16x8*)(k0 + 32 * KLD + 16);
;     bf16x8 pf[4];
;     u32x4 pk[4];
;     float ps = 0.f;
; #pragma unroll
;     for (int ks = 0; ks < NKS; ++ks) {
;       if (ks + 2 < NKS) {
;         ka[(ks + 2) % 3][0] = *(const bf16x8*)(k0 + 16 * (ks + 2));
;         ka[(ks + 2) % 3][1] = *(const bf16x8*)(k0 + 32 * KLD + 16 * (ks + 2));
;       }
;       __builtin_amdgcn_sched_barrier(0);
;       n0 = MFMA32(ka[ks % 3][0], qf[ks], n0); n1 = MFMA32(ka[ks % 3][1], qf[ks], n1);
;       {
;         constexpr int dummy0 = 0; (void)dummy0;
;         const int e_lo = (32 * ks) / NKS, e_hi = (32 * (ks + 1)) / NKS;
; #pragma unroll
;         for (int q = 0; q < 3; ++q) {
;           const int e = e_lo + q;
;           if (e < e_hi) {
;             if (e < 16) { s0[e & 15] = ex2(fmaf(s0[e & 15], c, -mc)); ps += s0[e & 15]; }
;             else        { s1[e & 15] = ex2(fmaf(s1[e & 15], c, -mc)); ps += s1[e & 15]; }
;           }
;         }
;       }
;       if (ks == 3)  { pk[0].x = pack2(s0[0], s0[1]);  pk[0].y = pack2(s0[2], s0[3]);   pk[0].z = pack2(s0[4], s0[5]);   pk[0].w = pack2(s0[6], s0[7]); }
;       if (ks == 6)  { pk[1].x = pack2(s0[8], s0[9]);  pk[1].y = pack2(s0[10], s0[11]); pk[1].z = pack2(s0[12], s0[13]); pk[1].w = pack2(s0[14], s0[15]); }
;       if (ks == 9)  { pk[2].x = pack2(s1[0], s1[1]);  pk[2].y = pack2(s1[2], s1[3]);   pk[2].z = pack2(s1[4], s1[5]);   pk[2].w = pack2(s1[6], s1[7]); }
;       if (ks == NKS - 1) { pk[3].x = pack2(s1[8], s1[9]);  pk[3].y = pack2(s1[10], s1[11]); pk[3].z = pack2(s1[12], s1[13]); pk[3].w = pack2(s1[14], s1[15]); }
;       __builtin_amdgcn_sched_barrier(0);
;     }
;     l += ps;
; #pragma unroll
;     for (int i = 0; i < 4; ++i) pf[i] = __builtin_bit_cast(bf16x8, pk[i]);
.LBB0_268:
	ds_read_b128 v[16:19], v212
	ds_read_b128 v[20:23], v212 offset:32
	ds_read_b128 v[24:27], v212 offset:12800
	ds_read_b128 v[28:31], v212 offset:64
	ds_read_b128 v[48:51], v212 offset:12832
	ds_read_b128 v[52:55], v212 offset:12864
	v_accvgpr_read_b32 v56, a238
	v_mul_f32_e32 v249, 0xbdd53b94, v216
	v_cmp_le_i32_e32 vcc, s45, v56
	s_waitcnt lgkmcnt(5)
	v_mfma_f32_32x32x16_bf16 a[80:95], v[16:19], v[96:99], 0
	v_fmamk_f32 v16, v32, 0x3dd53b94, v249
	v_exp_f32_e32 v191, v16
	v_fmamk_f32 v16, v33, 0x3dd53b94, v249
	v_exp_f32_e32 v192, v16
	s_waitcnt lgkmcnt(3)
	v_mfma_f32_32x32x16_bf16 a[64:79], v[24:27], v[96:99], 0
	ds_read_b128 v[16:19], v212 offset:96
	ds_read_b128 v[24:27], v212 offset:12896
	v_mfma_f32_32x32x16_bf16 a[80:95], v[20:23], v[100:103], a[80:95]
	v_fmamk_f32 v20, v34, 0x3dd53b94, v249
	v_exp_f32_e32 v193, v20
	v_fmamk_f32 v20, v35, 0x3dd53b94, v249
	v_exp_f32_e32 v198, v20
	v_fmamk_f32 v20, v36, 0x3dd53b94, v249
	v_exp_f32_e32 v199, v20
	s_waitcnt lgkmcnt(3)
	v_mfma_f32_32x32x16_bf16 a[64:79], v[48:51], v[100:103], a[64:79]
	ds_read_b128 v[20:23], v212 offset:128
	ds_read_b128 v[32:35], v212 offset:12928
	v_mfma_f32_32x32x16_bf16 a[80:95], v[28:31], v[104:107], a[80:95]
	v_fmamk_f32 v28, v37, 0x3dd53b94, v249
	v_exp_f32_e32 v200, v28
	v_fmamk_f32 v28, v38, 0x3dd53b94, v249
	v_exp_f32_e32 v201, v28
	v_fmamk_f32 v28, v39, 0x3dd53b94, v249
	v_exp_f32_e32 v202, v28
	s_waitcnt lgkmcnt(4)
	v_mfma_f32_32x32x16_bf16 a[64:79], v[52:55], v[104:107], a[64:79]
	ds_read_b128 v[28:31], v212 offset:160
	ds_read_b128 v[36:39], v212 offset:12960
	s_waitcnt lgkmcnt(5)
	v_mfma_f32_32x32x16_bf16 a[80:95], v[16:19], v[108:111], a[80:95]
	v_fmamk_f32 v16, v40, 0x3dd53b94, v249
	v_exp_f32_e32 v203, v16
	v_fmamk_f32 v16, v41, 0x3dd53b94, v249
	v_exp_f32_e32 v204, v16
	s_waitcnt lgkmcnt(4)
	v_mfma_f32_32x32x16_bf16 a[64:79], v[24:27], v[108:111], a[64:79]
	ds_read_b128 v[16:19], v212 offset:192
	ds_read_b128 v[24:27], v212 offset:12992
	s_waitcnt lgkmcnt(5)
	v_mfma_f32_32x32x16_bf16 a[80:95], v[20:23], v[112:115], a[80:95]
	v_fmamk_f32 v20, v42, 0x3dd53b94, v249
	v_exp_f32_e32 v205, v20
	v_fmamk_f32 v20, v43, 0x3dd53b94, v249
	v_exp_f32_e32 v206, v20
	v_fmamk_f32 v20, v44, 0x3dd53b94, v249
	v_exp_f32_e32 v207, v20
	s_waitcnt lgkmcnt(4)
	v_mfma_f32_32x32x16_bf16 a[64:79], v[32:35], v[112:115], a[64:79]
	ds_read_b128 v[20:23], v212 offset:224
	ds_read_b128 v[32:35], v212 offset:13024
	s_waitcnt lgkmcnt(5)
	v_mfma_f32_32x32x16_bf16 a[80:95], v[28:31], v[116:119], a[80:95]
	v_fmamk_f32 v28, v45, 0x3dd53b94, v249
	v_exp_f32_e32 v208, v28
	v_fmamk_f32 v28, v46, 0x3dd53b94, v249
	v_exp_f32_e32 v209, v28
	v_fmamk_f32 v28, v47, 0x3dd53b94, v249
	v_exp_f32_e32 v248, v28
	s_waitcnt lgkmcnt(4)
	v_mfma_f32_32x32x16_bf16 a[64:79], v[36:39], v[116:119], a[64:79]
	ds_read_b128 v[28:31], v212 offset:256
	ds_read_b128 v[36:39], v212 offset:13056
	s_waitcnt lgkmcnt(5)
	v_mfma_f32_32x32x16_bf16 a[80:95], v[16:19], v[120:123], a[80:95]
	v_fmamk_f32 v0, v0, 0x3dd53b94, v249
	v_exp_f32_e32 v213, v0
	v_fmamk_f32 v0, v1, 0x3dd53b94, v249
	v_exp_f32_e32 v214, v0
	s_waitcnt lgkmcnt(4)
	v_mfma_f32_32x32x16_bf16 a[64:79], v[24:27], v[120:123], a[64:79]
	ds_read_b128 v[16:19], v212 offset:288
	ds_read_b128 v[24:27], v212 offset:13088
	s_waitcnt lgkmcnt(5)
	v_mfma_f32_32x32x16_bf16 a[80:95], v[20:23], v[124:127], a[80:95]
	v_fmamk_f32 v0, v2, 0x3dd53b94, v249
	v_exp_f32_e32 v129, v0
	v_fmamk_f32 v0, v3, 0x3dd53b94, v249
	v_exp_f32_e32 v215, v0
	v_fmamk_f32 v0, v4, 0x3dd53b94, v249
	v_exp_f32_e32 v227, v0
	s_waitcnt lgkmcnt(4)
	v_mfma_f32_32x32x16_bf16 a[64:79], v[32:35], v[124:127], a[64:79]
	ds_read_b128 v[0:3], v212 offset:320
	ds_read_b128 v[20:23], v212 offset:13120
	s_waitcnt lgkmcnt(5)
	v_mfma_f32_32x32x16_bf16 a[80:95], v[28:31], v[130:133], a[80:95]
	v_fmamk_f32 v4, v5, 0x3dd53b94, v249
	v_exp_f32_e32 v228, v4
	v_fmamk_f32 v4, v6, 0x3dd53b94, v249
	v_exp_f32_e32 v229, v4
	v_fmamk_f32 v4, v7, 0x3dd53b94, v249
	v_exp_f32_e32 v230, v4
	s_waitcnt lgkmcnt(4)
	v_mfma_f32_32x32x16_bf16 a[64:79], v[36:39], v[130:133], a[64:79]
	ds_read_b128 v[4:7], v212 offset:352
	ds_read_b128 v[28:31], v212 offset:13152
	s_waitcnt lgkmcnt(5)
	v_mfma_f32_32x32x16_bf16 a[80:95], v[16:19], v[134:137], a[80:95]
	v_fmamk_f32 v8, v8, 0x3dd53b94, v249
	v_exp_f32_e32 v149, v8
	v_fmamk_f32 v8, v9, 0x3dd53b94, v249
	v_exp_f32_e32 v218, v8
	s_waitcnt lgkmcnt(4)
	v_mfma_f32_32x32x16_bf16 a[64:79], v[24:27], v[134:137], a[64:79]
	s_waitcnt lgkmcnt(3)
	v_mfma_f32_32x32x16_bf16 a[80:95], v[0:3], v[138:141], a[80:95]
	v_fmamk_f32 v0, v10, 0x3dd53b94, v249
	v_exp_f32_e32 v231, v0
	v_fmamk_f32 v0, v11, 0x3dd53b94, v249
	v_exp_f32_e32 v235, v0
	v_fmamk_f32 v0, v12, 0x3dd53b94, v249
	v_exp_f32_e32 v244, v0
	s_waitcnt lgkmcnt(2)
	v_mfma_f32_32x32x16_bf16 a[64:79], v[20:23], v[138:141], a[64:79]
	s_waitcnt lgkmcnt(1)
	v_mfma_f32_32x32x16_bf16 a[80:95], v[4:7], v[142:145], a[80:95]
	v_fmamk_f32 v0, v13, 0x3dd53b94, v249
	v_exp_f32_e32 v146, v0
	v_fmamk_f32 v0, v14, 0x3dd53b94, v249
	v_exp_f32_e32 v147, v0
	v_fmamk_f32 v0, v15, 0x3dd53b94, v249
	v_exp_f32_e32 v148, v0
	s_waitcnt lgkmcnt(0)
	v_mfma_f32_32x32x16_bf16 a[64:79], v[28:31], v[142:145], a[64:79]
	v_add_u32_e32 v211, 0x1000, v220
	v_add_u32_e32 v251, 0x2000, v220
	v_add_u32_e32 v210, 0x3000, v220
	s_and_saveexec_b64 s[0:1], vcc
	s_xor_b64 s[0:1], exec, s[0:1]
	s_cbranch_execz .LBB0_270
; template <int DQK>
; DI void attn_item_c(const u16* __restrict__ Qp, int ldq, const u16* __restrict__ Kp, const u16* __restrict__ Vtp, int ldv,
;                     int nkt, int q0, float c, u16* Yp, int ldy, char* smem, bool dry) {
;     ...
;   auto gload = [&](u32x4* ks_, u32x4* vs_, int j) {
;     const u16* kg = Kp + (size_t)(j + 1) * 64 * DQK;
; #pragma unroll
;     for (int i = 0; i < NKC; ++i) ks_[i] = *(const u32x4*)(kg + (size_t)(tid + 256 * i) * 8);
; #pragma unroll
;     for (int i = 0; i < 4; ++i) vs_[i] = *(const u32x4*)(Vtp + (size_t)j * 8192 + (size_t)(tid + 256 * i) * 8);
;   };
;   auto lstore = [&](const u32x4* ks_, const u32x4* vs_, u16* Lb) {
; #pragma unroll
;     for (int i = 0; i < NKC; ++i) *(u32x4*)(Lb + kso[i]) = ks_[i];
; #pragma unroll
;     for (int i = 0; i < 4; ++i) {
;       u16* dst = Lb + vso + (32 * i) * 72;
;       u32x2 lo = {vs_[i].x, vs_[i].y}, hi = {vs_[i].z, vs_[i].w};
;       *(u32x2*)dst = lo; *(u32x2*)(dst + 8) = hi;
;     }
;   };
;   auto gloadK = [&](u32x4* ks_, int j) {
;     const u16* kg = Kp + (size_t)(j + 1) * 64 * DQK;
; #pragma unroll
;     for (int i = 0; i < NKC; ++i) ks_[i] = *(const u32x4*)(kg + (size_t)(tid + 256 * i) * 8);
;   };
;   auto gloadV = [&](u32x4* vs_, int j) {
; #pragma unroll
;     for (int i = 0; i < 4; ++i) vs_[i] = *(const u32x4*)(Vtp + (size_t)j * 8192 + (size_t)(tid + 256 * i) * 8);
;   };
;   auto lstoreK = [&](const u32x4* ks_, u16* Lb) {
; #pragma unroll
;     ...
;     if (active) {
;       const u16* v0 = Vs + r * 72 + 8 * h;
;       bf16x8 va[2][4];
; #pragma unroll
;       for (int dt = 0; dt < 4; ++dt) va[0][dt] = *(const bf16x8*)(v0 + (32 * dt) * 72);
; #pragma unroll
;       for (int kk = 0; kk < 4; ++kk) {
;         if (kk < 3) {
; #pragma unroll
;           for (int dt = 0; dt < 4; ++dt) va[(kk + 1) & 1][dt] = *(const bf16x8*)(v0 + (32 * dt) * 72 + 16 * (kk + 1));
;         }
;         __builtin_amdgcn_sched_barrier(0);
; #pragma unroll
;         for (int dt = 0; dt < 4; ++dt) o[dt] = MFMA32(va[kk & 1][dt], pf[kk], o[dt]);
;         if (kk == 0) lstoreK(wk, Ln);
;         if (kk == 1) lstoreV(wv, Ln);
;         if (kk == 2) gloadK(wk, kt + 3);
;         if (kk == 3) gloadV(wv, kt + 3);
;         __builtin_amdgcn_sched_barrier(0);
;       }
;     } else {
;       lstore(wk, wv, Ln);
;       gload(wk, wv, kt + 3);
;     }
	ds_read_b128 v[16:19], v128 offset:25600
	ds_read_b128 v[20:23], v128 offset:25632
	ds_read_b128 v[24:27], v128 offset:30208
	ds_read_b128 v[28:31], v128 offset:30240
	ds_read_b128 v[32:35], v128 offset:34816
	ds_read_b128 v[36:39], v128 offset:34848
	ds_read_b128 v[40:43], v128 offset:39424
	ds_read_b128 v[44:47], v128 offset:39456
	s_or_b32 s20, s44, 3
	s_add_i32 s8, s44, 4
	v_cvt_pk_bf16_f32 v0, v149, v218
	v_cvt_pk_bf16_f32 v1, v231, v235
	v_cvt_pk_bf16_f32 v2, v244, v146
	v_cvt_pk_bf16_f32 v3, v147, v148
	v_cvt_pk_bf16_f32 v4, v213, v214
	v_cvt_pk_bf16_f32 v5, v129, v215
	v_cvt_pk_bf16_f32 v6, v227, v228
	v_cvt_pk_bf16_f32 v7, v229, v230
	v_cvt_pk_bf16_f32 v8, v203, v204
	v_cvt_pk_bf16_f32 v9, v205, v206
	v_cvt_pk_bf16_f32 v10, v207, v208
	v_cvt_pk_bf16_f32 v11, v209, v248
	v_cvt_pk_bf16_f32 v12, v191, v192
	v_cvt_pk_bf16_f32 v13, v193, v198
	v_cvt_pk_bf16_f32 v14, v199, v200
	v_cvt_pk_bf16_f32 v15, v201, v202
	s_lshl_b64 s[6:7], s[20:21], 14
	s_mul_hi_u32 s9, s8, 0x6000
	s_mulk_i32 s8, 0x6000
	s_waitcnt lgkmcnt(7)
	v_mfma_f32_32x32x16_bf16 a[0:15], v[16:19], v[12:15], a[0:15]
	s_waitcnt vmcnt(10)
	ds_write_b128 v221, a[96:99] offset:44032
	ds_write_b128 v222, a[100:103] offset:44032
	ds_write_b128 v223, a[104:107] offset:44032
	ds_write_b128 v224, a[108:111] offset:44032
	ds_write_b128 v225, a[112:115] offset:44032
	ds_write_b128 v226, a[116:119] offset:44032
	s_waitcnt lgkmcnt(11)
	v_mfma_f32_32x32x16_bf16 a[16:31], v[24:27], v[12:15], a[16:31]
	s_waitcnt lgkmcnt(9)
	v_mfma_f32_32x32x16_bf16 a[32:47], v[32:35], v[12:15], a[32:47]
	s_waitcnt lgkmcnt(7)
	v_mfma_f32_32x32x16_bf16 a[48:63], v[40:43], v[12:15], a[48:63]
	ds_read_b128 v[12:15], v128 offset:25664
	ds_read_b128 v[16:19], v128 offset:30272
	ds_read_b128 v[24:27], v128 offset:34880
	ds_read_b128 v[32:35], v128 offset:39488
	v_mfma_f32_32x32x16_bf16 a[0:15], v[20:23], v[8:11], a[0:15]
	v_accvgpr_read_b32 v20, a240
	v_accvgpr_read_b32 v21, a241
	v_accvgpr_read_b32 v22, a242
	v_accvgpr_read_b32 v23, a243
	ds_write2_b64 v220, v[20:21], v[22:23] offset1:2
	ds_write2_b64 v211, v[150:151], v[152:153] offset0:64 offset1:66
	ds_write2_b64 v251, v[154:155], v[156:157] offset0:128 offset1:130
	ds_write2_b64 v210, v[158:159], v[160:161] offset0:192 offset1:194
	v_mfma_f32_32x32x16_bf16 a[16:31], v[28:31], v[8:11], a[16:31]
	v_mfma_f32_32x32x16_bf16 a[32:47], v[36:39], v[8:11], a[32:47]
	s_waitcnt lgkmcnt(14)
	v_mfma_f32_32x32x16_bf16 a[48:63], v[44:47], v[8:11], a[48:63]
	ds_read_b128 v[8:11], v128 offset:25696
	ds_read_b128 v[20:23], v128 offset:30304
	ds_read_b128 v[28:31], v128 offset:34912
	ds_read_b128 v[36:39], v128 offset:39520
	s_add_u32 s8, s94, s8
	s_addc_u32 s9, s95, s9
	s_waitcnt lgkmcnt(11)
	v_mfma_f32_32x32x16_bf16 a[0:15], v[12:15], v[4:7], a[0:15]
	global_load_dwordx4 a[148:151], v236, s[8:9]
	global_load_dwordx4 a[152:155], v238, s[8:9]
	global_load_dwordx4 a[160:163], v240, s[8:9]
	global_load_dwordx4 a[168:171], v242, s[8:9]
	v_accvgpr_read_b32 v12, a230
	v_accvgpr_read_b32 v14, a232
	global_load_dwordx4 a[176:179], v12, s[8:9]
	global_load_dwordx4 a[184:187], v14, s[8:9]
	s_waitcnt lgkmcnt(10)
	v_mfma_f32_32x32x16_bf16 a[16:31], v[16:19], v[4:7], a[16:31]
	s_waitcnt lgkmcnt(9)
	v_mfma_f32_32x32x16_bf16 a[32:47], v[24:27], v[4:7], a[32:47]
	s_waitcnt lgkmcnt(8)
	v_mfma_f32_32x32x16_bf16 a[48:63], v[32:35], v[4:7], a[48:63]
	s_add_u32 s6, s60, s6
	s_addc_u32 s7, s61, s7
	s_waitcnt lgkmcnt(3)
	v_mfma_f32_32x32x16_bf16 a[0:15], v[8:11], v[0:3], a[0:15]
	s_waitcnt lgkmcnt(2)
	v_mfma_f32_32x32x16_bf16 a[16:31], v[20:23], v[0:3], a[16:31]
	s_waitcnt lgkmcnt(1)
	v_mfma_f32_32x32x16_bf16 a[32:47], v[28:31], v[0:3], a[32:47]
	s_waitcnt lgkmcnt(0)
	v_mfma_f32_32x32x16_bf16 a[48:63], v[36:39], v[0:3], a[48:63]
	global_load_dwordx4 v[178:181], v236, s[6:7]
	global_load_dwordx4 v[186:189], v238, s[6:7]
	global_load_dwordx4 v[182:185], v240, s[6:7]
	global_load_dwordx4 v[194:197], v242, s[6:7]

; template <int DQK>
; DI void attn_item_c(const u16* __restrict__ Qp, int ldq, const u16* __restrict__ Kp, const u16* __restrict__ Vtp, int ldv,
;                     int nkt, int q0, float c, u16* Yp, int ldy, char* smem, bool dry) {
;     ...
;   auto body = [&](int kt, u32x4* wk, u32x4* wv, f32x16& s0, f32x16& s1, f32x16& n0, f32x16& n1) {
;     const u16* Ks = L0 + (kt & 1) * BUFE;
;     const u16* Vs = Ks + 64 * KLD;
;     u16* Ln = L0 + ((kt + 1) & 1) * BUFE;
;     const bool active = !(kt * 64 > qmin + 31);
;     if (kt * 64 + 63 > qmin) {
; #pragma unroll
;       for (int e = 0; e < 16; ++e) {
;         int key = kt * 64 + crow(e, h);
;         if (key > qi) s0[e] = -INFINITY;
;         if (key + 32 > qi) s1[e] = -INFINITY;
;       }
;     }
;     float mx = fmaxf(s0[0], s1[0]);
; #pragma unroll
;     for (int e = 1; e < 16; ++e) mx = fmaxf(fmaxf(mx, s0[e]), s1[e]);
;     mx = fmaxf(mx, __shfl_xor(mx, 32));
;     if (__builtin_amdgcn_ballot_w64((mx - m) * c > 8.f) != 0ull) {
;       const float mn = fmaxf(m, mx);
;       const float alpha = ex2((m - mn) * c);
;       m = mn;
;       l *= alpha;
; #pragma unroll
;       for (int dt = 0; dt < 4; ++dt)
; #pragma unroll
;         for (int e = 0; e < 16; ++e) o[dt][e] *= alpha;
;     }
;     const float mc = m * c;
; #pragma unroll
;     for (int e = 0; e < 16; ++e) { n0[e] = 0.f; n1[e] = 0.f; }
;     const u16* k0 = Ks + r * KLD + 8 * h;
;     bf16x8 ka[3][2];
;     ka[0][0] = *(const bf16x8*)(k0); ka[0][1] = *(const bf16x8*)(k0 + 32 * KLD);
;     ka[1][0] = *(const bf16x8*)(k0 + 16); ka[1][1] = *(const bf16x8*)(k0 + 32 * KLD + 16);
;     bf16x8 pf[4];
;     u32x4 pk[4];
;     float ps = 0.f;
; #pragma unroll
;     for (int ks = 0; ks < NKS; ++ks) {
;       if (ks + 2 < NKS) {
;         ka[(ks + 2) % 3][0] = *(const bf16x8*)(k0 + 16 * (ks + 2));
;         ka[(ks + 2) % 3][1] = *(const bf16x8*)(k0 + 32 * KLD + 16 * (ks + 2));
;       }
;       __builtin_amdgcn_sched_barrier(0);
;       n0 = MFMA32(ka[ks % 3][0], qf[ks], n0); n1 = MFMA32(ka[ks % 3][1], qf[ks], n1);
;       {
;         constexpr int dummy0 = 0; (void)dummy0;
;         const int e_lo = (32 * ks) / NKS, e_hi = (32 * (ks + 1)) / NKS;
; #pragma unroll
;         for (int q = 0; q < 3; ++q) {
;           const int e = e_lo + q;
;           if (e < e_hi) {
;             if (e < 16) { s0[e & 15] = ex2(fmaf(s0[e & 15], c, -mc)); ps += s0[e & 15]; }
.LBB0_278:
	ds_read_b128 v[18:21], v219 offset:44032
	ds_read_b128 v[22:25], v219 offset:44064
	ds_read_b128 v[26:29], v219 offset:56832
	ds_read_b128 v[48:51], v219 offset:44096
	ds_read_b128 v[52:55], v219 offset:56864
	ds_read_b128 v[56:59], v219 offset:56896
	v_accvgpr_read_b32 v17, a238
	v_mov_b32_e32 v16, v249
	v_cmp_le_i32_e32 vcc, s20, v17
	s_waitcnt lgkmcnt(5)
	v_mfma_f32_32x32x16_bf16 a[80:95], v[18:21], v[96:99], 0
	v_fmamk_f32 v17, v32, 0x3dd53b94, v16
	v_exp_f32_e32 v147, v17
	v_fmamk_f32 v17, v33, 0x3dd53b94, v16
	v_exp_f32_e32 v148, v17
	s_waitcnt lgkmcnt(3)
	v_mfma_f32_32x32x16_bf16 a[64:79], v[26:29], v[96:99], 0
	ds_read_b128 v[18:21], v219 offset:44128
	ds_read_b128 v[26:29], v219 offset:56928
	v_mfma_f32_32x32x16_bf16 a[80:95], v[22:25], v[100:103], a[80:95]
	v_fmamk_f32 v17, v34, 0x3dd53b94, v16
	v_exp_f32_e32 v149, v17
	v_fmamk_f32 v17, v35, 0x3dd53b94, v16
	v_exp_f32_e32 v150, v17
	v_fmamk_f32 v17, v36, 0x3dd53b94, v16
	v_exp_f32_e32 v151, v17
	s_waitcnt lgkmcnt(3)
	v_mfma_f32_32x32x16_bf16 a[64:79], v[52:55], v[100:103], a[64:79]
	ds_read_b128 v[22:25], v219 offset:44160
	ds_read_b128 v[30:33], v219 offset:56960
	v_mfma_f32_32x32x16_bf16 a[80:95], v[48:51], v[104:107], a[80:95]
	v_fmamk_f32 v17, v37, 0x3dd53b94, v16
	v_exp_f32_e32 v152, v17
	v_fmamk_f32 v17, v38, 0x3dd53b94, v16
	v_exp_f32_e32 v153, v17
	v_fmamk_f32 v17, v39, 0x3dd53b94, v16
	v_exp_f32_e32 v154, v17
	s_waitcnt lgkmcnt(4)
	v_mfma_f32_32x32x16_bf16 a[64:79], v[56:59], v[104:107], a[64:79]
	ds_read_b128 v[34:37], v219 offset:44192
	ds_read_b128 v[48:51], v219 offset:56992
	s_waitcnt lgkmcnt(5)
	v_mfma_f32_32x32x16_bf16 a[80:95], v[18:21], v[108:111], a[80:95]
	v_fmamk_f32 v17, v40, 0x3dd53b94, v16
	v_exp_f32_e32 v155, v17
	v_fmamk_f32 v17, v41, 0x3dd53b94, v16
	v_exp_f32_e32 v156, v17
	s_waitcnt lgkmcnt(4)
	v_mfma_f32_32x32x16_bf16 a[64:79], v[26:29], v[108:111], a[64:79]
	ds_read_b128 v[18:21], v219 offset:44224
	ds_read_b128 v[26:29], v219 offset:57024
	s_waitcnt lgkmcnt(5)
	v_mfma_f32_32x32x16_bf16 a[80:95], v[22:25], v[112:115], a[80:95]
	v_fmamk_f32 v17, v42, 0x3dd53b94, v16
	v_exp_f32_e32 v157, v17
	v_fmamk_f32 v17, v43, 0x3dd53b94, v16
	v_exp_f32_e32 v158, v17
	v_fmamk_f32 v17, v44, 0x3dd53b94, v16
	v_exp_f32_e32 v159, v17
	s_waitcnt lgkmcnt(4)
	v_mfma_f32_32x32x16_bf16 a[64:79], v[30:33], v[112:115], a[64:79]
	ds_read_b128 v[22:25], v219 offset:44256
	ds_read_b128 v[30:33], v219 offset:57056
	s_waitcnt lgkmcnt(5)
	v_mfma_f32_32x32x16_bf16 a[80:95], v[34:37], v[116:119], a[80:95]
	v_fmamk_f32 v17, v45, 0x3dd53b94, v16
	v_exp_f32_e32 v160, v17
	v_fmamk_f32 v17, v46, 0x3dd53b94, v16
	v_exp_f32_e32 v161, v17
	v_fmamk_f32 v17, v47, 0x3dd53b94, v16
	v_exp_f32_e32 v248, v17
	s_waitcnt lgkmcnt(4)
	v_mfma_f32_32x32x16_bf16 a[64:79], v[48:51], v[116:119], a[64:79]
	ds_read_b128 v[34:37], v219 offset:44288
	ds_read_b128 v[38:41], v219 offset:57088
	s_waitcnt lgkmcnt(5)
	v_mfma_f32_32x32x16_bf16 a[80:95], v[18:21], v[120:123], a[80:95]
	v_fmamk_f32 v0, v0, 0x3dd53b94, v16
	v_exp_f32_e32 v213, v0
	v_fmamk_f32 v0, v1, 0x3dd53b94, v16
	v_exp_f32_e32 v214, v0
	s_waitcnt lgkmcnt(4)
	v_mfma_f32_32x32x16_bf16 a[64:79], v[26:29], v[120:123], a[64:79]
	ds_read_b128 v[18:21], v219 offset:44320
	ds_read_b128 v[26:29], v219 offset:57120
	s_waitcnt lgkmcnt(5)
	v_mfma_f32_32x32x16_bf16 a[80:95], v[22:25], v[124:127], a[80:95]
	v_fmamk_f32 v0, v2, 0x3dd53b94, v16
	v_exp_f32_e32 v129, v0
	v_fmamk_f32 v0, v3, 0x3dd53b94, v16
	v_exp_f32_e32 v215, v0
	v_fmamk_f32 v0, v4, 0x3dd53b94, v16
	v_exp_f32_e32 v227, v0
	s_waitcnt lgkmcnt(4)
	v_mfma_f32_32x32x16_bf16 a[64:79], v[30:33], v[124:127], a[64:79]
	ds_read_b128 v[0:3], v219 offset:44352
	ds_read_b128 v[22:25], v219 offset:57152
	s_waitcnt lgkmcnt(5)
	v_mfma_f32_32x32x16_bf16 a[80:95], v[34:37], v[130:133], a[80:95]
	v_fmamk_f32 v4, v5, 0x3dd53b94, v16
	v_exp_f32_e32 v228, v4
	v_fmamk_f32 v4, v6, 0x3dd53b94, v16
	v_exp_f32_e32 v229, v4
	v_fmamk_f32 v4, v7, 0x3dd53b94, v16
	v_exp_f32_e32 v230, v4
	s_waitcnt lgkmcnt(4)
	v_mfma_f32_32x32x16_bf16 a[64:79], v[38:41], v[130:133], a[64:79]
	ds_read_b128 v[4:7], v219 offset:44384
	ds_read_b128 v[30:33], v219 offset:57184
	s_waitcnt lgkmcnt(5)
	v_mfma_f32_32x32x16_bf16 a[80:95], v[18:21], v[134:137], a[80:95]
	v_fmamk_f32 v8, v8, 0x3dd53b94, v16
	v_exp_f32_e32 v244, v8
	v_fmamk_f32 v8, v9, 0x3dd53b94, v16
	v_exp_f32_e32 v245, v8
	s_waitcnt lgkmcnt(4)
	v_mfma_f32_32x32x16_bf16 a[64:79], v[26:29], v[134:137], a[64:79]
	s_waitcnt lgkmcnt(3)
	v_mfma_f32_32x32x16_bf16 a[80:95], v[0:3], v[138:141], a[80:95]
	v_fmamk_f32 v0, v10, 0x3dd53b94, v16
	v_exp_f32_e32 v246, v0
	v_fmamk_f32 v0, v11, 0x3dd53b94, v16
	v_exp_f32_e32 v247, v0
	v_fmamk_f32 v0, v12, 0x3dd53b94, v16
	v_exp_f32_e32 v162, v0
	s_waitcnt lgkmcnt(2)
	v_mfma_f32_32x32x16_bf16 a[64:79], v[22:25], v[138:141], a[64:79]
	s_waitcnt lgkmcnt(1)
	v_mfma_f32_32x32x16_bf16 a[80:95], v[4:7], v[142:145], a[80:95]
	v_fmamk_f32 v0, v13, 0x3dd53b94, v16
	v_exp_f32_e32 v231, v0
	v_fmamk_f32 v0, v14, 0x3dd53b94, v16
	v_fmac_f32_e32 v16, 0x3dd53b94, v15
	v_exp_f32_e32 v235, v0
	v_exp_f32_e32 v218, v16
	s_waitcnt lgkmcnt(0)
	v_mfma_f32_32x32x16_bf16 a[64:79], v[30:33], v[142:145], a[64:79]
	s_and_saveexec_b64 s[0:1], vcc
	s_xor_b64 s[0:1], exec, s[0:1]
	s_cbranch_execz .LBB0_280
; template <int DQK>
; DI void attn_item_c(const u16* __restrict__ Qp, int ldq, const u16* __restrict__ Kp, const u16* __restrict__ Vtp, int ldv,
;                     int nkt, int q0, float c, u16* Yp, int ldy, char* smem, bool dry) {
;     ...
;   auto gload = [&](u32x4* ks_, u32x4* vs_, int j) {
;     const u16* kg = Kp + (size_t)(j + 1) * 64 * DQK;
; #pragma unroll
;     for (int i = 0; i < NKC; ++i) ks_[i] = *(const u32x4*)(kg + (size_t)(tid + 256 * i) * 8);
; #pragma unroll
;     for (int i = 0; i < 4; ++i) vs_[i] = *(const u32x4*)(Vtp + (size_t)j * 8192 + (size_t)(tid + 256 * i) * 8);
;   };
;   auto lstore = [&](const u32x4* ks_, const u32x4* vs_, u16* Lb) {
; #pragma unroll
;     for (int i = 0; i < NKC; ++i) *(u32x4*)(Lb + kso[i]) = ks_[i];
; #pragma unroll
;     for (int i = 0; i < 4; ++i) {
;       u16* dst = Lb + vso + (32 * i) * 72;
;       u32x2 lo = {vs_[i].x, vs_[i].y}, hi = {vs_[i].z, vs_[i].w};
;       *(u32x2*)dst = lo; *(u32x2*)(dst + 8) = hi;
;     }
;   };
;   auto gloadK = [&](u32x4* ks_, int j) {
;     const u16* kg = Kp + (size_t)(j + 1) * 64 * DQK;
; #pragma unroll
;     for (int i = 0; i < NKC; ++i) ks_[i] = *(const u32x4*)(kg + (size_t)(tid + 256 * i) * 8);
;   };
;   auto gloadV = [&](u32x4* vs_, int j) {
; #pragma unroll
;     for (int i = 0; i < 4; ++i) vs_[i] = *(const u32x4*)(Vtp + (size_t)j * 8192 + (size_t)(tid + 256 * i) * 8);
;   };
;   auto lstoreK = [&](const u32x4* ks_, u16* Lb) {
; #pragma unroll
;     ...
;     if (active) {
;       const u16* v0 = Vs + r * 72 + 8 * h;
;       bf16x8 va[2][4];
; #pragma unroll
;       for (int dt = 0; dt < 4; ++dt) va[0][dt] = *(const bf16x8*)(v0 + (32 * dt) * 72);
; #pragma unroll
;       for (int kk = 0; kk < 4; ++kk) {
;         if (kk < 3) {
; #pragma unroll
;           for (int dt = 0; dt < 4; ++dt) va[(kk + 1) & 1][dt] = *(const bf16x8*)(v0 + (32 * dt) * 72 + 16 * (kk + 1));
;         }
;         __builtin_amdgcn_sched_barrier(0);
; #pragma unroll
;         for (int dt = 0; dt < 4; ++dt) o[dt] = MFMA32(va[kk & 1][dt], pf[kk], o[dt]);
;         if (kk == 0) lstoreK(wk, Ln);
;         if (kk == 1) lstoreV(wv, Ln);
;         if (kk == 2) gloadK(wk, kt + 3);
;         if (kk == 3) gloadV(wv, kt + 3);
;         __builtin_amdgcn_sched_barrier(0);
;       }
;     } else {
;       lstore(wk, wv, Ln);
;       gload(wk, wv, kt + 3);
;     }
	ds_read_b128 v[16:19], v250
	ds_read_b128 v[20:23], v250 offset:32
	ds_read_b128 v[24:27], v250 offset:4608
	ds_read_b128 v[28:31], v250 offset:4640
	ds_read_b128 v[32:35], v250 offset:9216
	ds_read_b128 v[36:39], v250 offset:9248
	ds_read_b128 v[40:43], v250 offset:13824
	ds_read_b128 v[44:47], v250 offset:13856
	s_add_i32 s20, s44, 4
	s_add_i32 s8, s44, 5
	v_cvt_pk_bf16_f32 v0, v244, v245
	v_cvt_pk_bf16_f32 v1, v246, v247
	v_cvt_pk_bf16_f32 v2, v162, v231
	v_cvt_pk_bf16_f32 v3, v235, v218
	v_cvt_pk_bf16_f32 v4, v213, v214
	v_cvt_pk_bf16_f32 v5, v129, v215
	v_cvt_pk_bf16_f32 v6, v227, v228
	v_cvt_pk_bf16_f32 v7, v229, v230
	v_cvt_pk_bf16_f32 v8, v155, v156
	v_cvt_pk_bf16_f32 v9, v157, v158
	v_cvt_pk_bf16_f32 v10, v159, v160
	v_cvt_pk_bf16_f32 v11, v161, v248
	v_cvt_pk_bf16_f32 v12, v147, v148
	v_cvt_pk_bf16_f32 v13, v149, v150
	v_cvt_pk_bf16_f32 v14, v151, v152
	v_cvt_pk_bf16_f32 v15, v153, v154
	s_lshl_b64 s[6:7], s[20:21], 14
	s_mul_hi_u32 s9, s8, 0x6000
	s_mulk_i32 s8, 0x6000
	s_waitcnt lgkmcnt(7)
	v_mfma_f32_32x32x16_bf16 a[0:15], v[16:19], v[12:15], a[0:15]
	s_waitcnt vmcnt(10)
	ds_write_b128 v221, a[120:123]
	ds_write_b128 v222, a[124:127]
	ds_write_b128 v223, a[132:135]
	ds_write_b128 v224, a[136:139]
	ds_write_b128 v225, a[140:143]
	ds_write_b128 v226, a[144:147]
	s_waitcnt lgkmcnt(11)
	v_mfma_f32_32x32x16_bf16 a[16:31], v[24:27], v[12:15], a[16:31]
	s_waitcnt lgkmcnt(9)
	v_mfma_f32_32x32x16_bf16 a[32:47], v[32:35], v[12:15], a[32:47]
	s_waitcnt lgkmcnt(7)
	v_mfma_f32_32x32x16_bf16 a[48:63], v[40:43], v[12:15], a[48:63]
	ds_read_b128 v[12:15], v250 offset:64
	ds_read_b128 v[16:19], v250 offset:4672
	ds_read_b128 v[24:27], v250 offset:9280
	ds_read_b128 v[32:35], v250 offset:13888
	v_mfma_f32_32x32x16_bf16 a[0:15], v[20:23], v[8:11], a[0:15]
	v_accvgpr_read_b32 v20, a229
	v_mfma_f32_32x32x16_bf16 a[16:31], v[28:31], v[8:11], a[16:31]
	v_accvgpr_read_b32 v28, a244
	v_accvgpr_read_b32 v29, a245
	v_accvgpr_read_b32 v30, a246
	v_accvgpr_read_b32 v31, a247
	ds_write2_b64 v20, v[28:29], v[30:31] offset0:128 offset1:130
	v_accvgpr_read_b32 v20, a234
	ds_write2_b64 v20, v[170:171], v[172:173] offset0:192 offset1:194
	v_mfma_f32_32x32x16_bf16 a[32:47], v[36:39], v[8:11], a[32:47]
	v_accvgpr_read_b32 v20, a235
	ds_write2_b64 v20, v[166:167], v[168:169] offset1:2
	v_accvgpr_read_b32 v20, a236
	ds_write2_b64 v20, v[174:175], v[176:177] offset0:64 offset1:66
	s_waitcnt lgkmcnt(14)
	v_mfma_f32_32x32x16_bf16 a[48:63], v[44:47], v[8:11], a[48:63]
	ds_read_b128 v[8:11], v250 offset:96
	ds_read_b128 v[20:23], v250 offset:4704
	ds_read_b128 v[28:31], v250 offset:9312
	ds_read_b128 v[36:39], v250 offset:13920
	s_add_u32 s8, s94, s8
	s_addc_u32 s9, s95, s9
	s_waitcnt lgkmcnt(11)
	v_mfma_f32_32x32x16_bf16 a[0:15], v[12:15], v[4:7], a[0:15]
	global_load_dwordx4 a[156:159], v236, s[8:9]
	global_load_dwordx4 a[164:167], v238, s[8:9]
	global_load_dwordx4 a[172:175], v240, s[8:9]
	global_load_dwordx4 a[180:183], v242, s[8:9]
	v_accvgpr_read_b32 v12, a230
	v_accvgpr_read_b32 v14, a232
	global_load_dwordx4 a[188:191], v12, s[8:9]
	global_load_dwordx4 a[192:195], v14, s[8:9]
	s_waitcnt lgkmcnt(10)
	v_mfma_f32_32x32x16_bf16 a[16:31], v[16:19], v[4:7], a[16:31]
	s_waitcnt lgkmcnt(9)
	v_mfma_f32_32x32x16_bf16 a[32:47], v[24:27], v[4:7], a[32:47]
	s_waitcnt lgkmcnt(8)
	v_mfma_f32_32x32x16_bf16 a[48:63], v[32:35], v[4:7], a[48:63]
	s_add_u32 s6, s60, s6
	s_addc_u32 s7, s61, s7
	s_waitcnt lgkmcnt(3)
	v_mfma_f32_32x32x16_bf16 a[0:15], v[8:11], v[0:3], a[0:15]
	s_waitcnt lgkmcnt(2)
	v_mfma_f32_32x32x16_bf16 a[16:31], v[20:23], v[0:3], a[16:31]
	s_waitcnt lgkmcnt(1)
	v_mfma_f32_32x32x16_bf16 a[32:47], v[28:31], v[0:3], a[32:47]
	s_waitcnt lgkmcnt(0)
	v_mfma_f32_32x32x16_bf16 a[48:63], v[36:39], v[0:3], a[48:63]
	global_load_dwordx4 v[190:193], v236, s[6:7]
	global_load_dwordx4 v[202:205], v238, s[6:7]
	global_load_dwordx4 v[198:201], v240, s[6:7]
	global_load_dwordx4 v[206:209], v242, s[6:7]

; #define MFMA32(a, b, c) __builtin_amdgcn_mfma_f32_32x32x16_bf16((a), (b), (c), 0, 0, 0)
; DI float ex2(float x) { return __builtin_amdgcn_exp2f(x); }
; template <int DQK>
; DI void attn_item_c(const u16* __restrict__ Qp, int ldq, const u16* __restrict__ Kp, const u16* __restrict__ Vtp, int ldv,
;                     int nkt, int q0, float c, u16* Yp, int ldy, char* smem, bool dry) {
;     ...
;     const u16* k0 = Ks + r * KLD + 8 * h;
;     bf16x8 ka[3][2];
;     ka[0][0] = *(const bf16x8*)(k0); ka[0][1] = *(const bf16x8*)(k0 + 32 * KLD);
;     ka[1][0] = *(const bf16x8*)(k0 + 16); ka[1][1] = *(const bf16x8*)(k0 + 32 * KLD + 16);
;     bf16x8 pf[4];
;     u32x4 pk[4];
;     float ps = 0.f;
; #pragma unroll
;     for (int ks = 0; ks < NKS; ++ks) {
;       if (ks + 2 < NKS) {
;         ka[(ks + 2) % 3][0] = *(const bf16x8*)(k0 + 16 * (ks + 2));
;         ka[(ks + 2) % 3][1] = *(const bf16x8*)(k0 + 32 * KLD + 16 * (ks + 2));
;       }
;       __builtin_amdgcn_sched_barrier(0);
;       n0 = MFMA32(ka[ks % 3][0], qf[ks], n0); n1 = MFMA32(ka[ks % 3][1], qf[ks], n1);
;       {
;         constexpr int dummy0 = 0; (void)dummy0;
;         const int e_lo = (32 * ks) / NKS, e_hi = (32 * (ks + 1)) / NKS;
; #pragma unroll
;         for (int q = 0; q < 3; ++q) {
;           const int e = e_lo + q;
;           if (e < e_hi) {
;             if (e < 16) { s0[e & 15] = ex2(fmaf(s0[e & 15], c, -mc)); ps += s0[e & 15]; }
;             else        { s1[e & 15] = ex2(fmaf(s1[e & 15], c, -mc)); ps += s1[e & 15]; }
;           }
;         }
;       }
;       if (ks == 3)  { pk[0].x = pack2(s0[0], s0[1]);  pk[0].y = pack2(s0[2], s0[3]);   pk[0].z = pack2(s0[4], s0[5]);   pk[0].w = pack2(s0[6], s0[7]); }
;       if (ks == 6)  { pk[1].x = pack2(s0[8], s0[9]);  pk[1].y = pack2(s0[10], s0[11]); pk[1].z = pack2(s0[12], s0[13]); pk[1].w = pack2(s0[14], s0[15]); }
;       if (ks == 9)  { pk[2].x = pack2(s1[0], s1[1]);  pk[2].y = pack2(s1[2], s1[3]);   pk[2].z = pack2(s1[4], s1[5]);   pk[2].w = pack2(s1[6], s1[7]); }
;       if (ks == NKS - 1) { pk[3].x = pack2(s1[8], s1[9]);  pk[3].y = pack2(s1[10], s1[11]); pk[3].z = pack2(s1[12], s1[13]); pk[3].w = pack2(s1[14], s1[15]); }
;       __builtin_amdgcn_sched_barrier(0);
;     }
;     l += ps;
; #pragma unroll
;     for (int i = 0; i < 4; ++i) pf[i] = __builtin_bit_cast(bf16x8, pk[i]);
.LBB0_288:
	ds_read_b128 v[16:19], v212
	ds_read_b128 v[20:23], v212 offset:32
	ds_read_b128 v[24:27], v212 offset:12800
	ds_read_b128 v[28:31], v212 offset:64
	ds_read_b128 v[48:51], v212 offset:12832
	ds_read_b128 v[52:55], v212 offset:12864
	v_accvgpr_read_b32 v56, a238
	v_cmp_le_i32_e32 vcc, s20, v56
	s_waitcnt lgkmcnt(5)
	v_mfma_f32_32x32x16_bf16 a[80:95], v[16:19], v[96:99], 0
	v_fmamk_f32 v16, v32, 0x3dd53b94, v249
	v_exp_f32_e32 v162, v16
	v_fmamk_f32 v16, v33, 0x3dd53b94, v249
	v_exp_f32_e32 v163, v16
	s_waitcnt lgkmcnt(3)
	v_mfma_f32_32x32x16_bf16 a[64:79], v[24:27], v[96:99], 0
	ds_read_b128 v[16:19], v212 offset:96
	ds_read_b128 v[24:27], v212 offset:12896
	v_mfma_f32_32x32x16_bf16 a[80:95], v[20:23], v[100:103], a[80:95]
	v_fmamk_f32 v20, v34, 0x3dd53b94, v249
	v_exp_f32_e32 v164, v20
	v_fmamk_f32 v20, v35, 0x3dd53b94, v249
	v_exp_f32_e32 v165, v20
	v_fmamk_f32 v20, v36, 0x3dd53b94, v249
	v_exp_f32_e32 v166, v20
	s_waitcnt lgkmcnt(3)
	v_mfma_f32_32x32x16_bf16 a[64:79], v[48:51], v[100:103], a[64:79]
	ds_read_b128 v[20:23], v212 offset:128
	ds_read_b128 v[32:35], v212 offset:12928
	v_mfma_f32_32x32x16_bf16 a[80:95], v[28:31], v[104:107], a[80:95]
	v_fmamk_f32 v28, v37, 0x3dd53b94, v249
	v_exp_f32_e32 v167, v28
	v_fmamk_f32 v28, v38, 0x3dd53b94, v249
	v_exp_f32_e32 v168, v28
	v_fmamk_f32 v28, v39, 0x3dd53b94, v249
	v_exp_f32_e32 v169, v28
	s_waitcnt lgkmcnt(4)
	v_mfma_f32_32x32x16_bf16 a[64:79], v[52:55], v[104:107], a[64:79]
	ds_read_b128 v[28:31], v212 offset:160
	ds_read_b128 v[36:39], v212 offset:12960
	s_waitcnt lgkmcnt(5)
	v_mfma_f32_32x32x16_bf16 a[80:95], v[16:19], v[108:111], a[80:95]
	v_fmamk_f32 v16, v40, 0x3dd53b94, v249
	v_exp_f32_e32 v170, v16
	v_fmamk_f32 v16, v41, 0x3dd53b94, v249
	v_exp_f32_e32 v171, v16
	s_waitcnt lgkmcnt(4)
	v_mfma_f32_32x32x16_bf16 a[64:79], v[24:27], v[108:111], a[64:79]
	ds_read_b128 v[16:19], v212 offset:192
	ds_read_b128 v[24:27], v212 offset:12992
	s_waitcnt lgkmcnt(5)
	v_mfma_f32_32x32x16_bf16 a[80:95], v[20:23], v[112:115], a[80:95]
	v_fmamk_f32 v20, v42, 0x3dd53b94, v249
	v_exp_f32_e32 v172, v20
	v_fmamk_f32 v20, v43, 0x3dd53b94, v249
	v_exp_f32_e32 v173, v20
	v_fmamk_f32 v20, v44, 0x3dd53b94, v249
	v_exp_f32_e32 v174, v20
	s_waitcnt lgkmcnt(4)
	v_mfma_f32_32x32x16_bf16 a[64:79], v[32:35], v[112:115], a[64:79]
	ds_read_b128 v[20:23], v212 offset:224
	ds_read_b128 v[32:35], v212 offset:13024
	s_waitcnt lgkmcnt(5)
	v_mfma_f32_32x32x16_bf16 a[80:95], v[28:31], v[116:119], a[80:95]
	v_fmamk_f32 v28, v45, 0x3dd53b94, v249
	v_exp_f32_e32 v175, v28
	v_fmamk_f32 v28, v46, 0x3dd53b94, v249
	v_exp_f32_e32 v176, v28
	v_fmamk_f32 v28, v47, 0x3dd53b94, v249
	v_exp_f32_e32 v177, v28
	s_waitcnt lgkmcnt(4)
	v_mfma_f32_32x32x16_bf16 a[64:79], v[36:39], v[116:119], a[64:79]
	ds_read_b128 v[28:31], v212 offset:256
	ds_read_b128 v[36:39], v212 offset:13056
	s_waitcnt lgkmcnt(5)
	v_mfma_f32_32x32x16_bf16 a[80:95], v[16:19], v[120:123], a[80:95]
	v_fmamk_f32 v0, v0, 0x3dd53b94, v249
	v_exp_f32_e32 v213, v0
	v_fmamk_f32 v0, v1, 0x3dd53b94, v249
	v_exp_f32_e32 v214, v0
	s_waitcnt lgkmcnt(4)
	v_mfma_f32_32x32x16_bf16 a[64:79], v[24:27], v[120:123], a[64:79]
	ds_read_b128 v[16:19], v212 offset:288
	ds_read_b128 v[24:27], v212 offset:13088
	s_waitcnt lgkmcnt(5)
	v_mfma_f32_32x32x16_bf16 a[80:95], v[20:23], v[124:127], a[80:95]
	v_fmamk_f32 v0, v2, 0x3dd53b94, v249
	v_exp_f32_e32 v215, v0
	v_fmamk_f32 v0, v3, 0x3dd53b94, v249
	v_exp_f32_e32 v129, v0
	v_fmamk_f32 v0, v4, 0x3dd53b94, v249
	v_exp_f32_e32 v227, v0
	s_waitcnt lgkmcnt(4)
	v_mfma_f32_32x32x16_bf16 a[64:79], v[32:35], v[124:127], a[64:79]
	ds_read_b128 v[0:3], v212 offset:320
	ds_read_b128 v[20:23], v212 offset:13120
	s_waitcnt lgkmcnt(5)
	v_mfma_f32_32x32x16_bf16 a[80:95], v[28:31], v[130:133], a[80:95]
	v_fmamk_f32 v4, v5, 0x3dd53b94, v249
	v_exp_f32_e32 v228, v4
	v_fmamk_f32 v4, v6, 0x3dd53b94, v249
	v_exp_f32_e32 v229, v4
	v_fmamk_f32 v4, v7, 0x3dd53b94, v249
	v_exp_f32_e32 v230, v4
	s_waitcnt lgkmcnt(4)
	v_mfma_f32_32x32x16_bf16 a[64:79], v[36:39], v[130:133], a[64:79]
	ds_read_b128 v[4:7], v212 offset:352
	ds_read_b128 v[28:31], v212 offset:13152
	s_waitcnt lgkmcnt(5)
	v_mfma_f32_32x32x16_bf16 a[80:95], v[16:19], v[134:137], a[80:95]
	v_fmamk_f32 v8, v8, 0x3dd53b94, v249
	v_exp_f32_e32 v147, v8
	v_fmamk_f32 v8, v9, 0x3dd53b94, v249
	v_exp_f32_e32 v148, v8
	s_waitcnt lgkmcnt(4)
	v_mfma_f32_32x32x16_bf16 a[64:79], v[24:27], v[134:137], a[64:79]
	s_waitcnt lgkmcnt(3)
	v_mfma_f32_32x32x16_bf16 a[80:95], v[0:3], v[138:141], a[80:95]
	v_fmamk_f32 v0, v10, 0x3dd53b94, v249
	v_exp_f32_e32 v149, v0
	v_fmamk_f32 v0, v11, 0x3dd53b94, v249
	v_exp_f32_e32 v218, v0
	v_fmamk_f32 v0, v12, 0x3dd53b94, v249
	v_exp_f32_e32 v244, v0
	s_waitcnt lgkmcnt(2)
	v_mfma_f32_32x32x16_bf16 a[64:79], v[20:23], v[138:141], a[64:79]
	s_waitcnt lgkmcnt(1)
	v_mfma_f32_32x32x16_bf16 a[80:95], v[4:7], v[142:145], a[80:95]
	v_fmamk_f32 v0, v13, 0x3dd53b94, v249
	v_exp_f32_e32 v231, v0
	v_fmamk_f32 v0, v14, 0x3dd53b94, v249
	v_exp_f32_e32 v235, v0
	v_fmamk_f32 v0, v15, 0x3dd53b94, v249
	v_exp_f32_e32 v146, v0
	s_waitcnt lgkmcnt(0)
	v_mfma_f32_32x32x16_bf16 a[64:79], v[28:31], v[142:145], a[64:79]
	s_and_saveexec_b64 s[0:1], vcc
	s_xor_b64 s[0:1], exec, s[0:1]
	s_cbranch_execz .LBB0_290
; template <int DQK>
; DI void attn_item_c(const u16* __restrict__ Qp, int ldq, const u16* __restrict__ Kp, const u16* __restrict__ Vtp, int ldv,
;                     int nkt, int q0, float c, u16* Yp, int ldy, char* smem, bool dry) {
;     ...
;   auto gload = [&](u32x4* ks_, u32x4* vs_, int j) {
;     const u16* kg = Kp + (size_t)(j + 1) * 64 * DQK;
; #pragma unroll
;     for (int i = 0; i < NKC; ++i) ks_[i] = *(const u32x4*)(kg + (size_t)(tid + 256 * i) * 8);
; #pragma unroll
;     for (int i = 0; i < 4; ++i) vs_[i] = *(const u32x4*)(Vtp + (size_t)j * 8192 + (size_t)(tid + 256 * i) * 8);
;   };
;   auto lstore = [&](const u32x4* ks_, const u32x4* vs_, u16* Lb) {
; #pragma unroll
;     for (int i = 0; i < NKC; ++i) *(u32x4*)(Lb + kso[i]) = ks_[i];
; #pragma unroll
;     for (int i = 0; i < 4; ++i) {
;       u16* dst = Lb + vso + (32 * i) * 72;
;       u32x2 lo = {vs_[i].x, vs_[i].y}, hi = {vs_[i].z, vs_[i].w};
;       *(u32x2*)dst = lo; *(u32x2*)(dst + 8) = hi;
;     }
;   };
;   auto gloadK = [&](u32x4* ks_, int j) {
;     const u16* kg = Kp + (size_t)(j + 1) * 64 * DQK;
; #pragma unroll
;     for (int i = 0; i < NKC; ++i) ks_[i] = *(const u32x4*)(kg + (size_t)(tid + 256 * i) * 8);
;   };
;   auto gloadV = [&](u32x4* vs_, int j) {
; #pragma unroll
;     for (int i = 0; i < 4; ++i) vs_[i] = *(const u32x4*)(Vtp + (size_t)j * 8192 + (size_t)(tid + 256 * i) * 8);
;   };
;   auto lstoreK = [&](const u32x4* ks_, u16* Lb) {
; #pragma unroll
;     ...
;     if (active) {
;       const u16* v0 = Vs + r * 72 + 8 * h;
;       bf16x8 va[2][4];
; #pragma unroll
;       for (int dt = 0; dt < 4; ++dt) va[0][dt] = *(const bf16x8*)(v0 + (32 * dt) * 72);
; #pragma unroll
;       for (int kk = 0; kk < 4; ++kk) {
;         if (kk < 3) {
; #pragma unroll
;           for (int dt = 0; dt < 4; ++dt) va[(kk + 1) & 1][dt] = *(const bf16x8*)(v0 + (32 * dt) * 72 + 16 * (kk + 1));
;         }
;         __builtin_amdgcn_sched_barrier(0);
; #pragma unroll
;         for (int dt = 0; dt < 4; ++dt) o[dt] = MFMA32(va[kk & 1][dt], pf[kk], o[dt]);
;         if (kk == 0) lstoreK(wk, Ln);
;         if (kk == 1) lstoreV(wv, Ln);
;         if (kk == 2) gloadK(wk, kt + 3);
;         if (kk == 3) gloadV(wv, kt + 3);
;         __builtin_amdgcn_sched_barrier(0);
;       }
;     } else {
;       lstore(wk, wv, Ln);
;       gload(wk, wv, kt + 3);
;     }
	ds_read_b128 v[16:19], v128 offset:25600
	ds_read_b128 v[20:23], v128 offset:25632
	ds_read_b128 v[24:27], v128 offset:30208
	ds_read_b128 v[28:31], v128 offset:30240
	ds_read_b128 v[32:35], v128 offset:34816
	ds_read_b128 v[36:39], v128 offset:34848
	ds_read_b128 v[40:43], v128 offset:39424
	ds_read_b128 v[44:47], v128 offset:39456
	s_add_i32 s20, s44, 5
	s_add_i32 s8, s44, 6
	v_cvt_pk_bf16_f32 v0, v147, v148
	v_cvt_pk_bf16_f32 v1, v149, v218
	v_cvt_pk_bf16_f32 v2, v244, v231
	v_cvt_pk_bf16_f32 v3, v235, v146
	v_cvt_pk_bf16_f32 v4, v213, v214
	v_cvt_pk_bf16_f32 v5, v215, v129
	v_cvt_pk_bf16_f32 v6, v227, v228
	v_cvt_pk_bf16_f32 v7, v229, v230
	v_cvt_pk_bf16_f32 v8, v170, v171
	v_cvt_pk_bf16_f32 v9, v172, v173
	v_cvt_pk_bf16_f32 v10, v174, v175
	v_cvt_pk_bf16_f32 v11, v176, v177
	v_cvt_pk_bf16_f32 v12, v162, v163
	v_cvt_pk_bf16_f32 v13, v164, v165
	v_cvt_pk_bf16_f32 v14, v166, v167
	v_cvt_pk_bf16_f32 v15, v168, v169
	s_lshl_b64 s[6:7], s[20:21], 14
	s_mul_hi_u32 s9, s8, 0x6000
	s_mulk_i32 s8, 0x6000
	s_waitcnt lgkmcnt(7)
	v_mfma_f32_32x32x16_bf16 a[0:15], v[16:19], v[12:15], a[0:15]
	s_waitcnt vmcnt(10)
	ds_write_b128 v221, a[148:151] offset:44032
	ds_write_b128 v222, a[152:155] offset:44032
	ds_write_b128 v223, a[160:163] offset:44032
	ds_write_b128 v224, a[168:171] offset:44032
	ds_write_b128 v225, a[176:179] offset:44032
	ds_write_b128 v226, a[184:187] offset:44032
	s_waitcnt lgkmcnt(11)
	v_mfma_f32_32x32x16_bf16 a[16:31], v[24:27], v[12:15], a[16:31]
	s_waitcnt lgkmcnt(9)
	v_mfma_f32_32x32x16_bf16 a[32:47], v[32:35], v[12:15], a[32:47]
	s_waitcnt lgkmcnt(7)
	v_mfma_f32_32x32x16_bf16 a[48:63], v[40:43], v[12:15], a[48:63]
	ds_read_b128 v[12:15], v128 offset:25664
	ds_read_b128 v[16:19], v128 offset:30272
	ds_read_b128 v[24:27], v128 offset:34880
	ds_read_b128 v[32:35], v128 offset:39488
	v_mfma_f32_32x32x16_bf16 a[0:15], v[20:23], v[8:11], a[0:15]
	ds_write2_b64 v220, v[178:179], v[180:181] offset1:2
	ds_write2_b64 v211, v[186:187], v[188:189] offset0:64 offset1:66
	ds_write2_b64 v251, v[182:183], v[184:185] offset0:128 offset1:130
	ds_write2_b64 v210, v[194:195], v[196:197] offset0:192 offset1:194
	v_mfma_f32_32x32x16_bf16 a[16:31], v[28:31], v[8:11], a[16:31]
	v_mfma_f32_32x32x16_bf16 a[32:47], v[36:39], v[8:11], a[32:47]
	s_waitcnt lgkmcnt(14)
	v_mfma_f32_32x32x16_bf16 a[48:63], v[44:47], v[8:11], a[48:63]
	ds_read_b128 v[8:11], v128 offset:25696
	ds_read_b128 v[20:23], v128 offset:30304
	ds_read_b128 v[28:31], v128 offset:34912
	ds_read_b128 v[36:39], v128 offset:39520
	s_add_u32 s8, s94, s8
	s_addc_u32 s9, s95, s9
	s_waitcnt lgkmcnt(11)
	v_mfma_f32_32x32x16_bf16 a[0:15], v[12:15], v[4:7], a[0:15]
	global_load_dwordx4 a[96:99], v236, s[8:9]
	global_load_dwordx4 a[100:103], v238, s[8:9]
	global_load_dwordx4 a[104:107], v240, s[8:9]
	global_load_dwordx4 a[108:111], v242, s[8:9]
	v_accvgpr_read_b32 v12, a230
	v_accvgpr_read_b32 v14, a232
	global_load_dwordx4 a[112:115], v12, s[8:9]
	global_load_dwordx4 a[116:119], v14, s[8:9]
	s_waitcnt lgkmcnt(10)
	v_mfma_f32_32x32x16_bf16 a[16:31], v[16:19], v[4:7], a[16:31]
	s_waitcnt lgkmcnt(9)
	v_mfma_f32_32x32x16_bf16 a[32:47], v[24:27], v[4:7], a[32:47]
	s_waitcnt lgkmcnt(8)
	v_mfma_f32_32x32x16_bf16 a[48:63], v[32:35], v[4:7], a[48:63]
	s_add_u32 s6, s60, s6
	s_addc_u32 s7, s61, s7
	s_waitcnt lgkmcnt(3)
	v_mfma_f32_32x32x16_bf16 a[0:15], v[8:11], v[0:3], a[0:15]
	s_waitcnt lgkmcnt(2)
	v_mfma_f32_32x32x16_bf16 a[16:31], v[20:23], v[0:3], a[16:31]
	s_waitcnt lgkmcnt(1)
	v_mfma_f32_32x32x16_bf16 a[32:47], v[28:31], v[0:3], a[32:47]
	s_waitcnt lgkmcnt(0)
	v_mfma_f32_32x32x16_bf16 a[48:63], v[36:39], v[0:3], a[48:63]
	global_load_dwordx4 a[240:243], v236, s[6:7]
	global_load_dwordx4 v[150:153], v238, s[6:7]
	global_load_dwordx4 v[154:157], v240, s[6:7]
	global_load_dwordx4 v[158:161], v242, s[6:7]

; #define MFMA32(a, b, c) __builtin_amdgcn_mfma_f32_32x32x16_bf16((a), (b), (c), 0, 0, 0)
; DI float ex2(float x) { return __builtin_amdgcn_exp2f(x); }
; template <int DQK>
; DI void attn_item_c(const u16* __restrict__ Qp, int ldq, const u16* __restrict__ Kp, const u16* __restrict__ Vtp, int ldv,
;                     int nkt, int q0, float c, u16* Yp, int ldy, char* smem, bool dry) {
;     ...
;     const u16* k0 = Ks + r * KLD + 8 * h;
;     bf16x8 ka[3][2];
;     ka[0][0] = *(const bf16x8*)(k0); ka[0][1] = *(const bf16x8*)(k0 + 32 * KLD);
;     ka[1][0] = *(const bf16x8*)(k0 + 16); ka[1][1] = *(const bf16x8*)(k0 + 32 * KLD + 16);
;     bf16x8 pf[4];
;     u32x4 pk[4];
;     float ps = 0.f;
; #pragma unroll
;     for (int ks = 0; ks < NKS; ++ks) {
;       if (ks + 2 < NKS) {
;         ka[(ks + 2) % 3][0] = *(const bf16x8*)(k0 + 16 * (ks + 2));
;         ka[(ks + 2) % 3][1] = *(const bf16x8*)(k0 + 32 * KLD + 16 * (ks + 2));
;       }
;       __builtin_amdgcn_sched_barrier(0);
;       n0 = MFMA32(ka[ks % 3][0], qf[ks], n0); n1 = MFMA32(ka[ks % 3][1], qf[ks], n1);
;       {
;         constexpr int dummy0 = 0; (void)dummy0;
;         const int e_lo = (32 * ks) / NKS, e_hi = (32 * (ks + 1)) / NKS;
; #pragma unroll
;         for (int q = 0; q < 3; ++q) {
;           const int e = e_lo + q;
;           if (e < e_hi) {
;             if (e < 16) { s0[e & 15] = ex2(fmaf(s0[e & 15], c, -mc)); ps += s0[e & 15]; }
;             else        { s1[e & 15] = ex2(fmaf(s1[e & 15], c, -mc)); ps += s1[e & 15]; }
;           }
;         }
;       }
;       if (ks == 3)  { pk[0].x = pack2(s0[0], s0[1]);  pk[0].y = pack2(s0[2], s0[3]);   pk[0].z = pack2(s0[4], s0[5]);   pk[0].w = pack2(s0[6], s0[7]); }
;       if (ks == 6)  { pk[1].x = pack2(s0[8], s0[9]);  pk[1].y = pack2(s0[10], s0[11]); pk[1].z = pack2(s0[12], s0[13]); pk[1].w = pack2(s0[14], s0[15]); }
;       if (ks == 9)  { pk[2].x = pack2(s1[0], s1[1]);  pk[2].y = pack2(s1[2], s1[3]);   pk[2].z = pack2(s1[4], s1[5]);   pk[2].w = pack2(s1[6], s1[7]); }
;       if (ks == NKS - 1) { pk[3].x = pack2(s1[8], s1[9]);  pk[3].y = pack2(s1[10], s1[11]); pk[3].z = pack2(s1[12], s1[13]); pk[3].w = pack2(s1[14], s1[15]); }
;       __builtin_amdgcn_sched_barrier(0);
;     }
;     l += ps;
; #pragma unroll
;     for (int i = 0; i < 4; ++i) pf[i] = __builtin_bit_cast(bf16x8, pk[i]);
.LBB0_298:
	ds_read_b128 v[16:19], v219 offset:44032
	ds_read_b128 v[20:23], v219 offset:44064
	ds_read_b128 v[24:27], v219 offset:56832
	ds_read_b128 v[28:31], v219 offset:44096
	ds_read_b128 v[48:51], v219 offset:56864
	ds_read_b128 v[52:55], v219 offset:56896
	v_accvgpr_read_b32 v56, a238
	v_cmp_le_i32_e32 vcc, s20, v56
	s_waitcnt lgkmcnt(5)
	v_mfma_f32_32x32x16_bf16 a[80:95], v[16:19], v[96:99], 0
	v_fmamk_f32 v16, v32, 0x3dd53b94, v249
	v_fmamk_f32 v17, v33, 0x3dd53b94, v249
	v_exp_f32_e32 v16, v16
	v_exp_f32_e32 v17, v17
	s_waitcnt lgkmcnt(3)
	v_mfma_f32_32x32x16_bf16 a[64:79], v[24:27], v[96:99], 0
	ds_read_b128 v[24:27], v219 offset:44128
	ds_read_b128 v[56:59], v219 offset:56928
	v_mfma_f32_32x32x16_bf16 a[80:95], v[20:23], v[100:103], a[80:95]
	v_fmamk_f32 v18, v34, 0x3dd53b94, v249
	v_fmamk_f32 v19, v35, 0x3dd53b94, v249
	v_fmamk_f32 v20, v36, 0x3dd53b94, v249
	v_exp_f32_e32 v18, v18
	v_exp_f32_e32 v19, v19
	v_exp_f32_e32 v20, v20
	s_waitcnt lgkmcnt(3)
	v_mfma_f32_32x32x16_bf16 a[64:79], v[48:51], v[100:103], a[64:79]
	ds_read_b128 v[32:35], v219 offset:44160
	ds_read_b128 v[48:51], v219 offset:56960
	v_mfma_f32_32x32x16_bf16 a[80:95], v[28:31], v[104:107], a[80:95]
	v_fmamk_f32 v21, v37, 0x3dd53b94, v249
	v_fmamk_f32 v22, v38, 0x3dd53b94, v249
	v_fmamk_f32 v23, v39, 0x3dd53b94, v249
	v_exp_f32_e32 v21, v21
	v_exp_f32_e32 v22, v22
	v_exp_f32_e32 v23, v23
	s_waitcnt lgkmcnt(4)
	v_mfma_f32_32x32x16_bf16 a[64:79], v[52:55], v[104:107], a[64:79]
	ds_read_b128 v[36:39], v219 offset:44192
	ds_read_b128 v[52:55], v219 offset:56992
	s_waitcnt lgkmcnt(5)
	v_mfma_f32_32x32x16_bf16 a[80:95], v[24:27], v[108:111], a[80:95]
	v_fmamk_f32 v24, v40, 0x3dd53b94, v249
	v_fmamk_f32 v25, v41, 0x3dd53b94, v249
	v_exp_f32_e32 v24, v24
	v_exp_f32_e32 v25, v25
	s_waitcnt lgkmcnt(4)
	v_mfma_f32_32x32x16_bf16 a[64:79], v[56:59], v[108:111], a[64:79]
	ds_read_b128 v[56:59], v219 offset:44224
	ds_read_b128 v[60:63], v219 offset:57024
	s_waitcnt lgkmcnt(5)
	v_mfma_f32_32x32x16_bf16 a[80:95], v[32:35], v[112:115], a[80:95]
	v_fmamk_f32 v26, v42, 0x3dd53b94, v249
	v_fmamk_f32 v27, v43, 0x3dd53b94, v249
	v_fmamk_f32 v28, v44, 0x3dd53b94, v249
	v_exp_f32_e32 v26, v26
	v_exp_f32_e32 v27, v27
	v_exp_f32_e32 v28, v28
	s_waitcnt lgkmcnt(4)
	v_mfma_f32_32x32x16_bf16 a[64:79], v[48:51], v[112:115], a[64:79]
	ds_read_b128 v[32:35], v219 offset:44256
	ds_read_b128 v[40:43], v219 offset:57056
	s_waitcnt lgkmcnt(5)
	v_mfma_f32_32x32x16_bf16 a[80:95], v[36:39], v[116:119], a[80:95]
	v_fmamk_f32 v29, v45, 0x3dd53b94, v249
	v_fmamk_f32 v30, v46, 0x3dd53b94, v249
	v_fmamk_f32 v31, v47, 0x3dd53b94, v249
	v_exp_f32_e32 v29, v29
	v_exp_f32_e32 v30, v30
	v_exp_f32_e32 v31, v31
	s_waitcnt lgkmcnt(4)
	v_mfma_f32_32x32x16_bf16 a[64:79], v[52:55], v[116:119], a[64:79]
	ds_read_b128 v[36:39], v219 offset:44288
	ds_read_b128 v[44:47], v219 offset:57088
	s_waitcnt lgkmcnt(5)
	v_mfma_f32_32x32x16_bf16 a[80:95], v[56:59], v[120:123], a[80:95]
	v_fmamk_f32 v0, v0, 0x3dd53b94, v249
	v_fmamk_f32 v1, v1, 0x3dd53b94, v249
	v_exp_f32_e32 v0, v0
	v_exp_f32_e32 v1, v1
	s_waitcnt lgkmcnt(4)
	v_mfma_f32_32x32x16_bf16 a[64:79], v[60:63], v[120:123], a[64:79]
	ds_read_b128 v[48:51], v219 offset:44320
	ds_read_b128 v[52:55], v219 offset:57120
	s_waitcnt lgkmcnt(5)
	v_mfma_f32_32x32x16_bf16 a[80:95], v[32:35], v[124:127], a[80:95]
	v_fmamk_f32 v2, v2, 0x3dd53b94, v249
	v_fmamk_f32 v3, v3, 0x3dd53b94, v249
	v_fmamk_f32 v4, v4, 0x3dd53b94, v249
	v_exp_f32_e32 v2, v2
	v_exp_f32_e32 v3, v3
	v_exp_f32_e32 v4, v4
	s_waitcnt lgkmcnt(4)
	v_mfma_f32_32x32x16_bf16 a[64:79], v[40:43], v[124:127], a[64:79]
	ds_read_b128 v[32:35], v219 offset:44352
	ds_read_b128 v[40:43], v219 offset:57152
	s_waitcnt lgkmcnt(5)
	v_mfma_f32_32x32x16_bf16 a[80:95], v[36:39], v[130:133], a[80:95]
	v_fmamk_f32 v5, v5, 0x3dd53b94, v249
	v_fmamk_f32 v6, v6, 0x3dd53b94, v249
	v_fmamk_f32 v7, v7, 0x3dd53b94, v249
	v_exp_f32_e32 v5, v5
	v_exp_f32_e32 v6, v6
	v_exp_f32_e32 v7, v7
	s_waitcnt lgkmcnt(4)
	v_mfma_f32_32x32x16_bf16 a[64:79], v[44:47], v[130:133], a[64:79]
	ds_read_b128 v[36:39], v219 offset:44384
	ds_read_b128 v[44:47], v219 offset:57184
	s_waitcnt lgkmcnt(5)
	v_mfma_f32_32x32x16_bf16 a[80:95], v[48:51], v[134:137], a[80:95]
	v_fmamk_f32 v8, v8, 0x3dd53b94, v249
	v_fmamk_f32 v9, v9, 0x3dd53b94, v249
	v_exp_f32_e32 v8, v8
	v_exp_f32_e32 v9, v9
	s_waitcnt lgkmcnt(4)
	v_mfma_f32_32x32x16_bf16 a[64:79], v[52:55], v[134:137], a[64:79]
	s_waitcnt lgkmcnt(3)
	v_mfma_f32_32x32x16_bf16 a[80:95], v[32:35], v[138:141], a[80:95]
	v_fmamk_f32 v10, v10, 0x3dd53b94, v249
	v_fmamk_f32 v11, v11, 0x3dd53b94, v249
	v_fmamk_f32 v12, v12, 0x3dd53b94, v249
	v_exp_f32_e32 v10, v10
	v_exp_f32_e32 v11, v11
	v_exp_f32_e32 v12, v12
	s_waitcnt lgkmcnt(2)
	v_mfma_f32_32x32x16_bf16 a[64:79], v[40:43], v[138:141], a[64:79]
	s_waitcnt lgkmcnt(1)
	v_mfma_f32_32x32x16_bf16 a[80:95], v[36:39], v[142:145], a[80:95]
	v_fmamk_f32 v13, v13, 0x3dd53b94, v249
	v_fmamk_f32 v14, v14, 0x3dd53b94, v249
	v_fmamk_f32 v15, v15, 0x3dd53b94, v249
	v_exp_f32_e32 v13, v13
	v_exp_f32_e32 v14, v14
	v_exp_f32_e32 v15, v15
	s_waitcnt lgkmcnt(0)
	v_mfma_f32_32x32x16_bf16 a[64:79], v[44:47], v[142:145], a[64:79]
	s_and_saveexec_b64 s[0:1], vcc
	s_xor_b64 s[0:1], exec, s[0:1]
	s_cbranch_execz .LBB0_300
; template <int DQK>
; DI void attn_item_c(const u16* __restrict__ Qp, int ldq, const u16* __restrict__ Kp, const u16* __restrict__ Vtp, int ldv,
;                     int nkt, int q0, float c, u16* Yp, int ldy, char* smem, bool dry) {
;     ...
;   auto gload = [&](u32x4* ks_, u32x4* vs_, int j) {
;     const u16* kg = Kp + (size_t)(j + 1) * 64 * DQK;
; #pragma unroll
;     for (int i = 0; i < NKC; ++i) ks_[i] = *(const u32x4*)(kg + (size_t)(tid + 256 * i) * 8);
; #pragma unroll
;     for (int i = 0; i < 4; ++i) vs_[i] = *(const u32x4*)(Vtp + (size_t)j * 8192 + (size_t)(tid + 256 * i) * 8);
;   };
;   auto lstore = [&](const u32x4* ks_, const u32x4* vs_, u16* Lb) {
; #pragma unroll
;     for (int i = 0; i < NKC; ++i) *(u32x4*)(Lb + kso[i]) = ks_[i];
; #pragma unroll
;     for (int i = 0; i < 4; ++i) {
;       u16* dst = Lb + vso + (32 * i) * 72;
;       u32x2 lo = {vs_[i].x, vs_[i].y}, hi = {vs_[i].z, vs_[i].w};
;       *(u32x2*)dst = lo; *(u32x2*)(dst + 8) = hi;
;     }
;   };
;   auto gloadK = [&](u32x4* ks_, int j) {
;     const u16* kg = Kp + (size_t)(j + 1) * 64 * DQK;
; #pragma unroll
;     for (int i = 0; i < NKC; ++i) ks_[i] = *(const u32x4*)(kg + (size_t)(tid + 256 * i) * 8);
;   };
;   auto gloadV = [&](u32x4* vs_, int j) {
; #pragma unroll
;     for (int i = 0; i < 4; ++i) vs_[i] = *(const u32x4*)(Vtp + (size_t)j * 8192 + (size_t)(tid + 256 * i) * 8);
;   };
;   auto lstoreK = [&](const u32x4* ks_, u16* Lb) {
; #pragma unroll
;     ...
;     if (active) {
;       const u16* v0 = Vs + r * 72 + 8 * h;
;       bf16x8 va[2][4];
; #pragma unroll
;       for (int dt = 0; dt < 4; ++dt) va[0][dt] = *(const bf16x8*)(v0 + (32 * dt) * 72);
; #pragma unroll
;       for (int kk = 0; kk < 4; ++kk) {
;         if (kk < 3) {
; #pragma unroll
;           for (int dt = 0; dt < 4; ++dt) va[(kk + 1) & 1][dt] = *(const bf16x8*)(v0 + (32 * dt) * 72 + 16 * (kk + 1));
;         }
;         __builtin_amdgcn_sched_barrier(0);
; #pragma unroll
;         for (int dt = 0; dt < 4; ++dt) o[dt] = MFMA32(va[kk & 1][dt], pf[kk], o[dt]);
;         if (kk == 0) lstoreK(wk, Ln);
;         if (kk == 1) lstoreV(wv, Ln);
;         if (kk == 2) gloadK(wk, kt + 3);
;         if (kk == 3) gloadV(wv, kt + 3);
;         __builtin_amdgcn_sched_barrier(0);
;       }
;     } else {
;       lstore(wk, wv, Ln);
;       gload(wk, wv, kt + 3);
;     }
	ds_read_b128 v[48:51], v250
	ds_read_b128 v[52:55], v250 offset:32
	ds_read_b128 v[56:59], v250 offset:4608
	ds_read_b128 v[60:63], v250 offset:4640
	ds_read_b128 v[64:67], v250 offset:9216
	ds_read_b128 v[68:71], v250 offset:9248
	ds_read_b128 v[72:75], v250 offset:13824
	ds_read_b128 v[76:79], v250 offset:13856
	s_add_i32 s20, s44, 6
	s_add_i32 s8, s44, 7
	v_cvt_pk_bf16_f32 v32, v8, v9
	v_cvt_pk_bf16_f32 v33, v10, v11
	v_cvt_pk_bf16_f32 v34, v12, v13
	v_cvt_pk_bf16_f32 v35, v14, v15
	v_cvt_pk_bf16_f32 v36, v0, v1
	v_cvt_pk_bf16_f32 v37, v2, v3
	v_cvt_pk_bf16_f32 v38, v4, v5
	v_cvt_pk_bf16_f32 v39, v6, v7
	v_cvt_pk_bf16_f32 v40, v24, v25
	v_cvt_pk_bf16_f32 v41, v26, v27
	v_cvt_pk_bf16_f32 v42, v28, v29
	v_cvt_pk_bf16_f32 v43, v30, v31
	v_cvt_pk_bf16_f32 v44, v16, v17
	v_cvt_pk_bf16_f32 v45, v18, v19
	v_cvt_pk_bf16_f32 v46, v20, v21
	v_cvt_pk_bf16_f32 v47, v22, v23
	s_lshl_b64 s[6:7], s[20:21], 14
	s_mul_hi_u32 s9, s8, 0x6000
	s_mulk_i32 s8, 0x6000
	s_waitcnt lgkmcnt(7)
	v_mfma_f32_32x32x16_bf16 a[0:15], v[48:51], v[44:47], a[0:15]
	s_waitcnt vmcnt(10)
	ds_write_b128 v221, a[156:159]
	ds_write_b128 v222, a[164:167]
	ds_write_b128 v223, a[172:175]
	ds_write_b128 v224, a[180:183]
	ds_write_b128 v225, a[188:191]
	ds_write_b128 v226, a[192:195]
	s_waitcnt lgkmcnt(11)
	v_mfma_f32_32x32x16_bf16 a[16:31], v[56:59], v[44:47], a[16:31]
	s_waitcnt lgkmcnt(9)
	v_mfma_f32_32x32x16_bf16 a[32:47], v[64:67], v[44:47], a[32:47]
	s_waitcnt lgkmcnt(7)
	v_mfma_f32_32x32x16_bf16 a[48:63], v[72:75], v[44:47], a[48:63]
	ds_read_b128 v[44:47], v250 offset:64
	ds_read_b128 v[48:51], v250 offset:4672
	ds_read_b128 v[56:59], v250 offset:9280
	ds_read_b128 v[64:67], v250 offset:13888
	v_mfma_f32_32x32x16_bf16 a[0:15], v[52:55], v[40:43], a[0:15]
	v_accvgpr_read_b32 v52, a229
	ds_write2_b64 v52, v[190:191], v[192:193] offset0:128 offset1:130
	v_accvgpr_read_b32 v52, a234
	ds_write2_b64 v52, v[202:203], v[204:205] offset0:192 offset1:194
	v_accvgpr_read_b32 v52, a235
	ds_write2_b64 v52, v[198:199], v[200:201] offset1:2
	v_accvgpr_read_b32 v52, a236
	v_mfma_f32_32x32x16_bf16 a[16:31], v[60:63], v[40:43], a[16:31]
	ds_write2_b64 v52, v[206:207], v[208:209] offset0:64 offset1:66
	v_mfma_f32_32x32x16_bf16 a[32:47], v[68:71], v[40:43], a[32:47]
	s_waitcnt lgkmcnt(14)
	v_mfma_f32_32x32x16_bf16 a[48:63], v[76:79], v[40:43], a[48:63]
	ds_read_b128 v[40:43], v250 offset:96
	ds_read_b128 v[52:55], v250 offset:4704
	ds_read_b128 v[60:63], v250 offset:9312
	ds_read_b128 v[68:71], v250 offset:13920
	s_add_u32 s8, s94, s8
	s_addc_u32 s9, s95, s9
	s_waitcnt lgkmcnt(11)
	v_mfma_f32_32x32x16_bf16 a[0:15], v[44:47], v[36:39], a[0:15]
	global_load_dwordx4 a[120:123], v236, s[8:9]
	global_load_dwordx4 a[124:127], v238, s[8:9]
	global_load_dwordx4 a[132:135], v240, s[8:9]
	global_load_dwordx4 a[136:139], v242, s[8:9]
	v_accvgpr_read_b32 v44, a230
	v_accvgpr_read_b32 v46, a232
	global_load_dwordx4 a[140:143], v44, s[8:9]
	global_load_dwordx4 a[144:147], v46, s[8:9]
	s_waitcnt lgkmcnt(10)
	v_mfma_f32_32x32x16_bf16 a[16:31], v[48:51], v[36:39], a[16:31]
	s_waitcnt lgkmcnt(9)
	v_mfma_f32_32x32x16_bf16 a[32:47], v[56:59], v[36:39], a[32:47]
	s_waitcnt lgkmcnt(8)
	v_mfma_f32_32x32x16_bf16 a[48:63], v[64:67], v[36:39], a[48:63]
	s_add_u32 s6, s60, s6
	s_addc_u32 s7, s61, s7
	s_waitcnt lgkmcnt(3)
	v_mfma_f32_32x32x16_bf16 a[0:15], v[40:43], v[32:35], a[0:15]
	s_waitcnt lgkmcnt(2)
	v_mfma_f32_32x32x16_bf16 a[16:31], v[52:55], v[32:35], a[16:31]
	s_waitcnt lgkmcnt(1)
	v_mfma_f32_32x32x16_bf16 a[32:47], v[60:63], v[32:35], a[32:47]
	s_waitcnt lgkmcnt(0)
	v_mfma_f32_32x32x16_bf16 a[48:63], v[68:71], v[32:35], a[48:63]
	global_load_dwordx4 a[244:247], v236, s[6:7]
	global_load_dwordx4 v[170:173], v238, s[6:7]
	global_load_dwordx4 v[166:169], v240, s[6:7]
	global_load_dwordx4 v[174:177], v242, s[6:7]
